# remove unit-transition vmcnt(0) in P7-P12, hoist P11 8th row-scale load, P12 epilogue 4-deep prefetch
# speedup vs baseline: 1.0025x; 1.0002x over previous
; template <class Epi, class Sched>
; __device__ __forceinline__ void gemm_phase(LAS unsigned char* lds, const Gemm g, const Sched& S, const Epi& E) {
;     ...
;         const bool has_next = S.next(ui + 1, nxt);
;         const char* nA = has_next ? (const char*)g.A + (size_t)nxt.pm * tstepA : cA; const char* nB = has_next ? (const char*)g.Bt + (size_t)nxt.pn * tstepB : cB;
;     ...
;         if (!has_next) break;
; #pragma unroll
;         for (int a = 0; a < 2; ++a)
; #pragma unroll
;             for (int b = 0; b < 2; ++b)
; #pragma unroll
;                 for (int m = 0; m < 4; ++m)
; #pragma unroll
;                     for (int n = 0; n < 2; ++n) acc[a][b][m][n] = (acc_t){0, 0, 0, 0};
;         cur = nxt; cA = nA; cB = nB; ++ui;
.LBB0_634:
	s_ashr_i32 s21, s20, 31
	v_cmp_lt_i64_e32 vcc, s[22:23], v[156:157]
	s_lshl_b64 s[22:23], s[20:21], 20
	v_readlane_b32 s24, v239, 25
	v_readlane_b32 s25, v239, 26
	s_add_u32 s22, s24, s22
	s_addc_u32 s23, s25, s23
	s_and_b64 s[24:25], vcc, exec
	s_cselect_b32 s21, s23, s29
	s_cselect_b32 s55, s22, s28
	s_ashr_i32 s19, s18, 31
	s_lshl_b64 s[24:25], s[18:19], 19
	s_add_u32 s24, s36, s24
	s_addc_u32 s25, s37, s25
	s_and_b64 s[34:35], vcc, exec
	s_cselect_b32 s19, s25, s31
	s_cselect_b32 s56, s24, s30
	s_add_u32 s28, s28, 0x80080
	s_addc_u32 s29, s29, 0
	s_add_u32 s57, s30, 0x100
	v_mov_b32_e32 v0, 0
	s_addc_u32 s58, s31, 0
	s_mov_b32 s59, -2
	v_mov_b32_e32 v1, v0
	v_mov_b32_e32 v2, v0
	v_mov_b32_e32 v3, v0
	v_mov_b32_e32 v4, v0
	v_mov_b32_e32 v5, v0
	v_mov_b32_e32 v6, v0
	v_mov_b32_e32 v7, v0
	v_mov_b32_e32 v16, v0
	v_mov_b32_e32 v17, v0
	v_mov_b32_e32 v18, v0
	v_mov_b32_e32 v19, v0
	v_mov_b32_e32 v20, v0
	v_mov_b32_e32 v21, v0
	v_mov_b32_e32 v22, v0
	v_mov_b32_e32 v23, v0
	v_mov_b32_e32 v32, v0
	v_mov_b32_e32 v33, v0
	v_mov_b32_e32 v34, v0
	v_mov_b32_e32 v35, v0
	v_mov_b32_e32 v36, v0
	v_mov_b32_e32 v37, v0
	v_mov_b32_e32 v38, v0
	v_mov_b32_e32 v39, v0
	v_mov_b32_e32 v48, v0
	v_mov_b32_e32 v49, v0
	v_mov_b32_e32 v50, v0
	v_mov_b32_e32 v51, v0
	v_mov_b32_e32 v52, v0
	v_mov_b32_e32 v53, v0
	v_mov_b32_e32 v54, v0
	v_mov_b32_e32 v55, v0
	v_mov_b32_e32 v8, v0
	v_mov_b32_e32 v9, v0
	v_mov_b32_e32 v10, v0
	v_mov_b32_e32 v11, v0
	v_mov_b32_e32 v12, v0
	v_mov_b32_e32 v13, v0
	v_mov_b32_e32 v14, v0
	v_mov_b32_e32 v15, v0
	v_mov_b32_e32 v24, v0
	v_mov_b32_e32 v25, v0
	v_mov_b32_e32 v26, v0
	v_mov_b32_e32 v27, v0
	v_mov_b32_e32 v28, v0
	v_mov_b32_e32 v29, v0
	v_mov_b32_e32 v30, v0
	v_mov_b32_e32 v31, v0
	v_mov_b32_e32 v40, v0
	v_mov_b32_e32 v41, v0
	v_mov_b32_e32 v42, v0
	v_mov_b32_e32 v43, v0
	v_mov_b32_e32 v44, v0
	v_mov_b32_e32 v45, v0
	v_mov_b32_e32 v46, v0
	v_mov_b32_e32 v47, v0
	v_mov_b32_e32 v64, v0
	v_mov_b32_e32 v65, v0
	v_mov_b32_e32 v66, v0
	v_mov_b32_e32 v67, v0
	v_mov_b32_e32 v68, v0
	v_mov_b32_e32 v69, v0
	v_mov_b32_e32 v70, v0
	v_mov_b32_e32 v71, v0
	v_mov_b32_e32 v80, v0
	v_mov_b32_e32 v81, v0
	v_mov_b32_e32 v82, v0
	v_mov_b32_e32 v83, v0
	v_mov_b32_e32 v84, v0
	v_mov_b32_e32 v85, v0
	v_mov_b32_e32 v86, v0
	v_mov_b32_e32 v87, v0
	v_mov_b32_e32 v96, v0
	v_mov_b32_e32 v97, v0
	v_mov_b32_e32 v98, v0
	v_mov_b32_e32 v99, v0
	v_mov_b32_e32 v100, v0
	v_mov_b32_e32 v101, v0
	v_mov_b32_e32 v102, v0
	v_mov_b32_e32 v103, v0
	v_mov_b32_e32 v112, v0
	v_mov_b32_e32 v113, v0
	v_mov_b32_e32 v114, v0
	v_mov_b32_e32 v115, v0
	v_mov_b32_e32 v116, v0
	v_mov_b32_e32 v117, v0
	v_mov_b32_e32 v118, v0
	v_mov_b32_e32 v119, v0
	v_mov_b32_e32 v128, v0
	v_mov_b32_e32 v129, v0
	v_mov_b32_e32 v130, v0
	v_mov_b32_e32 v131, v0
	v_mov_b32_e32 v132, v0
	v_mov_b32_e32 v133, v0
	v_mov_b32_e32 v134, v0
	v_mov_b32_e32 v135, v0
	v_mov_b32_e32 v88, v0
	v_mov_b32_e32 v89, v0
	v_mov_b32_e32 v90, v0
	v_mov_b32_e32 v91, v0
	v_mov_b32_e32 v92, v0
	v_mov_b32_e32 v93, v0
	v_mov_b32_e32 v94, v0
	v_mov_b32_e32 v95, v0
	v_mov_b32_e32 v104, v0
	v_mov_b32_e32 v105, v0
	v_mov_b32_e32 v106, v0
	v_mov_b32_e32 v107, v0
	v_mov_b32_e32 v108, v0
	v_mov_b32_e32 v109, v0
	v_mov_b32_e32 v110, v0
	v_mov_b32_e32 v111, v0
	v_mov_b32_e32 v120, v0
	v_mov_b32_e32 v121, v0
	v_mov_b32_e32 v122, v0
	v_mov_b32_e32 v123, v0
	v_mov_b32_e32 v124, v0
	v_mov_b32_e32 v125, v0
	v_mov_b32_e32 v126, v0
	v_mov_b32_e32 v127, v0
	v_mov_b32_e32 v136, v0
	v_mov_b32_e32 v137, v0
	v_mov_b32_e32 v138, v0
	v_mov_b32_e32 v139, v0
	v_mov_b32_e32 v140, v0
	v_mov_b32_e32 v141, v0
	v_mov_b32_e32 v142, v0
	v_mov_b32_e32 v143, v0

; template <class Epi, class Sched>
; __device__ __forceinline__ void gemm_phase(LAS unsigned char* lds, const Gemm g, const Sched& S, const Epi& E) {
;     ...
;         const bool has_next = S.next(ui + 1, nxt);
;         const char* nA = has_next ? (const char*)g.A + (size_t)nxt.pm * tstepA : cA; const char* nB = has_next ? (const char*)g.Bt + (size_t)nxt.pn * tstepB : cB;
;     ...
;         if (!has_next) break;
; #pragma unroll
;         for (int a = 0; a < 2; ++a)
; #pragma unroll
;             for (int b = 0; b < 2; ++b)
; #pragma unroll
;                 for (int m = 0; m < 4; ++m)
; #pragma unroll
;                     for (int n = 0; n < 2; ++n) acc[a][b][m][n] = (acc_t){0, 0, 0, 0};
;         cur = nxt; cA = nA; cB = nB; ++ui;
.LBB0_701:
	s_ashr_i32 s7, s6, 31
	v_cmp_lt_i64_e32 vcc, s[8:9], v[140:141]
	s_lshl_b64 s[8:9], s[6:7], 20
	v_readlane_b32 s5, v239, 48
	s_add_u32 s8, s5, s8
	v_readlane_b32 s5, v239, 49
	s_addc_u32 s9, s5, s9
	s_and_b64 s[10:11], vcc, exec
	s_cselect_b32 s7, s9, s15
	s_cselect_b32 s42, s8, s14
	s_ashr_i32 s5, s4, 31
	s_lshl_b64 s[10:11], s[4:5], 19
	v_readlane_b32 s18, v239, 40
	v_readlane_b32 s19, v239, 41
	s_add_u32 s10, s18, s10
	s_addc_u32 s11, s19, s11
	s_and_b64 s[18:19], vcc, exec
	s_cselect_b32 s5, s11, s17
	s_cselect_b32 s43, s10, s16
	s_add_u32 s14, s14, 0x80080
	s_addc_u32 s15, s15, 0
	s_add_u32 s44, s16, 0x100
	v_mov_b32_e32 v0, 0
	s_addc_u32 s45, s17, 0
	s_mov_b32 s46, -2
	v_mov_b32_e32 v1, v0
	v_mov_b32_e32 v2, v0
	v_mov_b32_e32 v3, v0
	v_mov_b32_e32 v4, v0
	v_mov_b32_e32 v5, v0
	v_mov_b32_e32 v6, v0
	v_mov_b32_e32 v7, v0
	v_mov_b32_e32 v12, v0
	v_mov_b32_e32 v13, v0
	v_mov_b32_e32 v14, v0
	v_mov_b32_e32 v15, v0
	v_mov_b32_e32 v20, v0
	v_mov_b32_e32 v21, v0
	v_mov_b32_e32 v22, v0
	v_mov_b32_e32 v23, v0
	v_mov_b32_e32 v32, v0
	v_mov_b32_e32 v33, v0
	v_mov_b32_e32 v34, v0
	v_mov_b32_e32 v35, v0
	v_mov_b32_e32 v36, v0
	v_mov_b32_e32 v37, v0
	v_mov_b32_e32 v38, v0
	v_mov_b32_e32 v39, v0
	v_mov_b32_e32 v44, v0
	v_mov_b32_e32 v45, v0
	v_mov_b32_e32 v46, v0
	v_mov_b32_e32 v47, v0
	v_mov_b32_e32 v52, v0
	v_mov_b32_e32 v53, v0
	v_mov_b32_e32 v54, v0
	v_mov_b32_e32 v55, v0
	v_mov_b32_e32 v8, v0
	v_mov_b32_e32 v9, v0
	v_mov_b32_e32 v10, v0
	v_mov_b32_e32 v11, v0
	v_mov_b32_e32 v16, v0
	v_mov_b32_e32 v17, v0
	v_mov_b32_e32 v18, v0
	v_mov_b32_e32 v19, v0
	v_mov_b32_e32 v24, v0
	v_mov_b32_e32 v25, v0
	v_mov_b32_e32 v26, v0
	v_mov_b32_e32 v27, v0
	v_mov_b32_e32 v28, v0
	v_mov_b32_e32 v29, v0
	v_mov_b32_e32 v30, v0
	v_mov_b32_e32 v31, v0
	v_mov_b32_e32 v40, v0
	v_mov_b32_e32 v41, v0
	v_mov_b32_e32 v42, v0
	v_mov_b32_e32 v43, v0
	v_mov_b32_e32 v48, v0
	v_mov_b32_e32 v49, v0
	v_mov_b32_e32 v50, v0
	v_mov_b32_e32 v51, v0
	v_mov_b32_e32 v56, v0
	v_mov_b32_e32 v57, v0
	v_mov_b32_e32 v58, v0
	v_mov_b32_e32 v59, v0
	v_mov_b32_e32 v60, v0
	v_mov_b32_e32 v61, v0
	v_mov_b32_e32 v62, v0
	v_mov_b32_e32 v63, v0
	v_mov_b32_e32 v64, v0
	v_mov_b32_e32 v65, v0
	v_mov_b32_e32 v66, v0
	v_mov_b32_e32 v67, v0
	v_mov_b32_e32 v68, v0
	v_mov_b32_e32 v69, v0
	v_mov_b32_e32 v70, v0
	v_mov_b32_e32 v71, v0
	v_mov_b32_e32 v80, v0
	v_mov_b32_e32 v81, v0
	v_mov_b32_e32 v82, v0
	v_mov_b32_e32 v83, v0
	v_mov_b32_e32 v84, v0
	v_mov_b32_e32 v85, v0
	v_mov_b32_e32 v86, v0
	v_mov_b32_e32 v87, v0
	v_mov_b32_e32 v96, v0
	v_mov_b32_e32 v97, v0
	v_mov_b32_e32 v98, v0
	v_mov_b32_e32 v99, v0
	v_mov_b32_e32 v100, v0
	v_mov_b32_e32 v101, v0
	v_mov_b32_e32 v102, v0
	v_mov_b32_e32 v103, v0
	v_mov_b32_e32 v112, v0
	v_mov_b32_e32 v113, v0
	v_mov_b32_e32 v114, v0
	v_mov_b32_e32 v115, v0
	v_mov_b32_e32 v116, v0
	v_mov_b32_e32 v117, v0
	v_mov_b32_e32 v118, v0
	v_mov_b32_e32 v119, v0
	v_mov_b32_e32 v72, v0
	v_mov_b32_e32 v73, v0
	v_mov_b32_e32 v74, v0
	v_mov_b32_e32 v75, v0
	v_mov_b32_e32 v76, v0
	v_mov_b32_e32 v77, v0
	v_mov_b32_e32 v78, v0
	v_mov_b32_e32 v79, v0
	v_mov_b32_e32 v88, v0
	v_mov_b32_e32 v89, v0
	v_mov_b32_e32 v90, v0
	v_mov_b32_e32 v91, v0
	v_mov_b32_e32 v92, v0
	v_mov_b32_e32 v93, v0
	v_mov_b32_e32 v94, v0
	v_mov_b32_e32 v95, v0
	v_mov_b32_e32 v104, v0
	v_mov_b32_e32 v105, v0
	v_mov_b32_e32 v106, v0
	v_mov_b32_e32 v107, v0
	v_mov_b32_e32 v108, v0
	v_mov_b32_e32 v109, v0
	v_mov_b32_e32 v110, v0
	v_mov_b32_e32 v111, v0
	v_mov_b32_e32 v120, v0
	v_mov_b32_e32 v121, v0
	v_mov_b32_e32 v122, v0
	v_mov_b32_e32 v123, v0
	v_mov_b32_e32 v124, v0
	v_mov_b32_e32 v125, v0
	v_mov_b32_e32 v126, v0
	v_mov_b32_e32 v127, v0

; template <class Epi, class Sched>
; __device__ __forceinline__ void gemm_phase(LAS unsigned char* lds, const Gemm g, const Sched& S, const Epi& E) {
;     ...
;         const bool has_next = S.next(ui + 1, nxt);
;         const char* nA = has_next ? (const char*)g.A + (size_t)nxt.pm * tstepA : cA; const char* nB = has_next ? (const char*)g.Bt + (size_t)nxt.pn * tstepB : cB;
;     ...
;         if (!has_next) break;
; #pragma unroll
;         for (int a = 0; a < 2; ++a)
; #pragma unroll
;             for (int b = 0; b < 2; ++b)
; #pragma unroll
;                 for (int m = 0; m < 4; ++m)
; #pragma unroll
;                     for (int n = 0; n < 2; ++n) acc[a][b][m][n] = (acc_t){0, 0, 0, 0};
;         cur = nxt; cA = nA; cB = nB; ++ui;
.LBB0_714:
	s_ashr_i32 s9, s8, 31
	v_cmp_lt_i64_e32 vcc, s[10:11], v[140:141]
	s_lshl_b64 s[10:11], s[8:9], 20
	s_add_u32 s10, s23, s10
	s_addc_u32 s11, s24, s11
	s_and_b64 s[12:13], vcc, exec
	s_cselect_b32 s9, s11, s17
	s_cselect_b32 s53, s10, s16
	s_ashr_i32 s7, s6, 31
	s_lshl_b64 s[12:13], s[6:7], 19
	v_readlane_b32 s20, v239, 42
	v_readlane_b32 s21, v239, 43
	s_add_u32 s12, s20, s12
	s_addc_u32 s13, s21, s13
	s_and_b64 s[20:21], vcc, exec
	s_cselect_b32 s7, s13, s19
	s_cselect_b32 s54, s12, s18
	s_add_u32 s16, s16, 0x80080
	s_addc_u32 s17, s17, 0
	s_add_u32 s55, s18, 0x100
	v_mov_b32_e32 v0, 0
	s_addc_u32 s56, s19, 0
	s_mov_b32 s57, -2
	v_mov_b32_e32 v1, v0
	v_mov_b32_e32 v2, v0
	v_mov_b32_e32 v3, v0
	v_mov_b32_e32 v4, v0
	v_mov_b32_e32 v5, v0
	v_mov_b32_e32 v6, v0
	v_mov_b32_e32 v7, v0
	v_mov_b32_e32 v12, v0
	v_mov_b32_e32 v13, v0
	v_mov_b32_e32 v14, v0
	v_mov_b32_e32 v15, v0
	v_mov_b32_e32 v20, v0
	v_mov_b32_e32 v21, v0
	v_mov_b32_e32 v22, v0
	v_mov_b32_e32 v23, v0
	v_mov_b32_e32 v32, v0
	v_mov_b32_e32 v33, v0
	v_mov_b32_e32 v34, v0
	v_mov_b32_e32 v35, v0
	v_mov_b32_e32 v36, v0
	v_mov_b32_e32 v37, v0
	v_mov_b32_e32 v38, v0
	v_mov_b32_e32 v39, v0
	v_mov_b32_e32 v48, v0
	v_mov_b32_e32 v49, v0
	v_mov_b32_e32 v50, v0
	v_mov_b32_e32 v51, v0
	v_mov_b32_e32 v52, v0
	v_mov_b32_e32 v53, v0
	v_mov_b32_e32 v54, v0
	v_mov_b32_e32 v55, v0
	v_mov_b32_e32 v8, v0
	v_mov_b32_e32 v9, v0
	v_mov_b32_e32 v10, v0
	v_mov_b32_e32 v11, v0
	v_mov_b32_e32 v16, v0
	v_mov_b32_e32 v17, v0
	v_mov_b32_e32 v18, v0
	v_mov_b32_e32 v19, v0
	v_mov_b32_e32 v24, v0
	v_mov_b32_e32 v25, v0
	v_mov_b32_e32 v26, v0
	v_mov_b32_e32 v27, v0
	v_mov_b32_e32 v28, v0
	v_mov_b32_e32 v29, v0
	v_mov_b32_e32 v30, v0
	v_mov_b32_e32 v31, v0
	v_mov_b32_e32 v40, v0
	v_mov_b32_e32 v41, v0
	v_mov_b32_e32 v42, v0
	v_mov_b32_e32 v43, v0
	v_mov_b32_e32 v44, v0
	v_mov_b32_e32 v45, v0
	v_mov_b32_e32 v46, v0
	v_mov_b32_e32 v47, v0
	v_mov_b32_e32 v56, v0
	v_mov_b32_e32 v57, v0
	v_mov_b32_e32 v58, v0
	v_mov_b32_e32 v59, v0
	v_mov_b32_e32 v60, v0
	v_mov_b32_e32 v61, v0
	v_mov_b32_e32 v62, v0
	v_mov_b32_e32 v63, v0
	v_mov_b32_e32 v64, v0
	v_mov_b32_e32 v65, v0
	v_mov_b32_e32 v66, v0
	v_mov_b32_e32 v67, v0
	v_mov_b32_e32 v68, v0
	v_mov_b32_e32 v69, v0
	v_mov_b32_e32 v70, v0
	v_mov_b32_e32 v71, v0
	v_mov_b32_e32 v80, v0
	v_mov_b32_e32 v81, v0
	v_mov_b32_e32 v82, v0
	v_mov_b32_e32 v83, v0
	v_mov_b32_e32 v84, v0
	v_mov_b32_e32 v85, v0
	v_mov_b32_e32 v86, v0
	v_mov_b32_e32 v87, v0
	v_mov_b32_e32 v96, v0
	v_mov_b32_e32 v97, v0
	v_mov_b32_e32 v98, v0
	v_mov_b32_e32 v99, v0
	v_mov_b32_e32 v100, v0
	v_mov_b32_e32 v101, v0
	v_mov_b32_e32 v102, v0
	v_mov_b32_e32 v103, v0
	v_mov_b32_e32 v112, v0
	v_mov_b32_e32 v113, v0
	v_mov_b32_e32 v114, v0
	v_mov_b32_e32 v115, v0
	v_mov_b32_e32 v116, v0
	v_mov_b32_e32 v117, v0
	v_mov_b32_e32 v118, v0
	v_mov_b32_e32 v119, v0
	v_mov_b32_e32 v72, v0
	v_mov_b32_e32 v73, v0
	v_mov_b32_e32 v74, v0
	v_mov_b32_e32 v75, v0
	v_mov_b32_e32 v76, v0
	v_mov_b32_e32 v77, v0
	v_mov_b32_e32 v78, v0
	v_mov_b32_e32 v79, v0
	v_mov_b32_e32 v88, v0
	v_mov_b32_e32 v89, v0
	v_mov_b32_e32 v90, v0
	v_mov_b32_e32 v91, v0
	v_mov_b32_e32 v92, v0
	v_mov_b32_e32 v93, v0
	v_mov_b32_e32 v94, v0
	v_mov_b32_e32 v95, v0
	v_mov_b32_e32 v104, v0
	v_mov_b32_e32 v105, v0
	v_mov_b32_e32 v106, v0
	v_mov_b32_e32 v107, v0
	v_mov_b32_e32 v108, v0
	v_mov_b32_e32 v109, v0
	v_mov_b32_e32 v110, v0
	v_mov_b32_e32 v111, v0
	v_mov_b32_e32 v120, v0
	v_mov_b32_e32 v121, v0
	v_mov_b32_e32 v122, v0
	v_mov_b32_e32 v123, v0
	v_mov_b32_e32 v124, v0
	v_mov_b32_e32 v125, v0
	v_mov_b32_e32 v126, v0
	v_mov_b32_e32 v127, v0

; template <class Epi, class Sched>
; __device__ __forceinline__ void gemm_phase(LAS unsigned char* lds, const Gemm g, const Sched& S, const Epi& E) {
;     ...
;         const bool has_next = S.next(ui + 1, nxt);
;         const char* nA = has_next ? (const char*)g.A + (size_t)nxt.pm * tstepA : cA; const char* nB = has_next ? (const char*)g.Bt + (size_t)nxt.pn * tstepB : cB;
;     ...
;         if (!has_next) break;
; #pragma unroll
;         for (int a = 0; a < 2; ++a)
; #pragma unroll
;             for (int b = 0; b < 2; ++b)
; #pragma unroll
;                 for (int m = 0; m < 4; ++m)
; #pragma unroll
;                     for (int n = 0; n < 2; ++n) acc[a][b][m][n] = (acc_t){0, 0, 0, 0};
;         cur = nxt; cA = nA; cB = nB; ++ui;
.LBB0_782:
	s_ashr_i32 s13, s12, 31
	v_cmp_lt_i64_e32 vcc, s[14:15], v[156:157]
	s_lshl_b64 s[14:15], s[12:13], 21
	s_add_u32 s14, s54, s14
	s_addc_u32 s15, s55, s15
	s_and_b64 s[16:17], vcc, exec
	s_cselect_b32 s13, s15, s21
	s_cselect_b32 s42, s14, s20
	s_ashr_i32 s11, s10, 31
	s_lshl_b64 s[16:17], s[10:11], 20
	v_readlane_b32 s24, v239, 44
	v_readlane_b32 s25, v239, 45
	s_add_u32 s16, s24, s16
	s_addc_u32 s17, s25, s17
	s_and_b64 s[24:25], vcc, exec
	s_cselect_b32 s11, s17, s23
	s_cselect_b32 s43, s16, s22
	s_add_u32 s20, s20, 0x100080
	s_addc_u32 s21, s21, 0
	s_add_u32 s44, s22, 0x100
	v_mov_b32_e32 v0, 0
	s_addc_u32 s45, s23, 0
	s_mov_b32 s46, -2
	s_waitcnt lgkmcnt(0)
	v_mov_b32_e32 v1, v0
	v_mov_b32_e32 v2, v0
	v_mov_b32_e32 v3, v0
	v_mov_b32_e32 v4, v0
	v_mov_b32_e32 v5, v0
	v_mov_b32_e32 v6, v0
	v_mov_b32_e32 v7, v0
	v_mov_b32_e32 v16, v0
	v_mov_b32_e32 v17, v0
	v_mov_b32_e32 v18, v0
	v_mov_b32_e32 v19, v0
	v_mov_b32_e32 v20, v0
	v_mov_b32_e32 v21, v0
	v_mov_b32_e32 v22, v0
	v_mov_b32_e32 v23, v0
	v_mov_b32_e32 v32, v0
	v_mov_b32_e32 v33, v0
	v_mov_b32_e32 v34, v0
	v_mov_b32_e32 v35, v0
	v_mov_b32_e32 v36, v0
	v_mov_b32_e32 v37, v0
	v_mov_b32_e32 v38, v0
	v_mov_b32_e32 v39, v0
	v_mov_b32_e32 v48, v0
	v_mov_b32_e32 v49, v0
	v_mov_b32_e32 v50, v0
	v_mov_b32_e32 v51, v0
	v_mov_b32_e32 v52, v0
	v_mov_b32_e32 v53, v0
	v_mov_b32_e32 v54, v0
	v_mov_b32_e32 v55, v0
	v_mov_b32_e32 v8, v0
	v_mov_b32_e32 v9, v0
	v_mov_b32_e32 v10, v0
	v_mov_b32_e32 v11, v0
	v_mov_b32_e32 v12, v0
	v_mov_b32_e32 v13, v0
	v_mov_b32_e32 v14, v0
	v_mov_b32_e32 v15, v0
	v_mov_b32_e32 v24, v0
	v_mov_b32_e32 v25, v0
	v_mov_b32_e32 v26, v0
	v_mov_b32_e32 v27, v0
	v_mov_b32_e32 v28, v0
	v_mov_b32_e32 v29, v0
	v_mov_b32_e32 v30, v0
	v_mov_b32_e32 v31, v0
	v_mov_b32_e32 v40, v0
	v_mov_b32_e32 v41, v0
	v_mov_b32_e32 v42, v0
	v_mov_b32_e32 v43, v0
	v_mov_b32_e32 v44, v0
	v_mov_b32_e32 v45, v0
	v_mov_b32_e32 v46, v0
	v_mov_b32_e32 v47, v0
	v_mov_b32_e32 v56, v0
	v_mov_b32_e32 v57, v0
	v_mov_b32_e32 v58, v0
	v_mov_b32_e32 v59, v0
	v_mov_b32_e32 v60, v0
	v_mov_b32_e32 v61, v0
	v_mov_b32_e32 v62, v0
	v_mov_b32_e32 v63, v0
	v_mov_b32_e32 v64, v0
	v_mov_b32_e32 v65, v0
	v_mov_b32_e32 v66, v0
	v_mov_b32_e32 v67, v0
	v_mov_b32_e32 v68, v0
	v_mov_b32_e32 v69, v0
	v_mov_b32_e32 v70, v0
	v_mov_b32_e32 v71, v0
	v_mov_b32_e32 v80, v0
	v_mov_b32_e32 v81, v0
	v_mov_b32_e32 v82, v0
	v_mov_b32_e32 v83, v0
	v_mov_b32_e32 v84, v0
	v_mov_b32_e32 v85, v0
	v_mov_b32_e32 v86, v0
	v_mov_b32_e32 v87, v0
	v_mov_b32_e32 v96, v0
	v_mov_b32_e32 v97, v0
	v_mov_b32_e32 v98, v0
	v_mov_b32_e32 v99, v0
	v_mov_b32_e32 v100, v0
	v_mov_b32_e32 v101, v0
	v_mov_b32_e32 v102, v0
	v_mov_b32_e32 v103, v0
	v_mov_b32_e32 v112, v0
	v_mov_b32_e32 v113, v0
	v_mov_b32_e32 v114, v0
	v_mov_b32_e32 v115, v0
	v_mov_b32_e32 v116, v0
	v_mov_b32_e32 v117, v0
	v_mov_b32_e32 v118, v0
	v_mov_b32_e32 v119, v0
	v_mov_b32_e32 v72, v0
	v_mov_b32_e32 v73, v0
	v_mov_b32_e32 v74, v0
	v_mov_b32_e32 v75, v0
	v_mov_b32_e32 v76, v0
	v_mov_b32_e32 v77, v0
	v_mov_b32_e32 v78, v0
	v_mov_b32_e32 v79, v0
	v_mov_b32_e32 v88, v0
	v_mov_b32_e32 v89, v0
	v_mov_b32_e32 v90, v0
	v_mov_b32_e32 v91, v0
	v_mov_b32_e32 v92, v0
	v_mov_b32_e32 v93, v0
	v_mov_b32_e32 v94, v0
	v_mov_b32_e32 v95, v0
	v_mov_b32_e32 v104, v0
	v_mov_b32_e32 v105, v0
	v_mov_b32_e32 v106, v0
	v_mov_b32_e32 v107, v0
	v_mov_b32_e32 v108, v0
	v_mov_b32_e32 v109, v0
	v_mov_b32_e32 v110, v0
	v_mov_b32_e32 v111, v0
	v_mov_b32_e32 v120, v0
	v_mov_b32_e32 v121, v0
	v_mov_b32_e32 v122, v0
	v_mov_b32_e32 v123, v0
	v_mov_b32_e32 v124, v0
	v_mov_b32_e32 v125, v0
	v_mov_b32_e32 v126, v0
	v_mov_b32_e32 v127, v0

; #define PG8_STAGE(bufoff, gbase, voff) do { _Pragma("unroll") for (int _i = 0; _i < 2; ++_i) \
;         __builtin_amdgcn_global_load_lds((const unsigned*)((const char*)(gbase) + (voff)[_i]), (LAS unsigned*)(lds + (bufoff) + ldsw + _i * 8192), 16, 0, 0); } while (0)
; #define PG8_LDA(dst, b, h) do { _Pragma("unroll") for (int m = 0; m < 4; ++m) _Pragma("unroll") for (int k = 0; k < 2; ++k) dst[m][k] = *(const LAS bf16x8*)(lds + PG8_SA(b, h) + aoff + m * 2048 + k * 1024); } while (0)
; #define PG8_LDB(dst, b, h) do { _Pragma("unroll") for (int n = 0; n < 2; ++n) _Pragma("unroll") for (int k = 0; k < 2; ++k) dst[n][k] = *(const LAS bf16x8*)(lds + PG8_SB(b, h) + boff + n * 2048 + k * 1024); } while (0)
; #define PG8_MMA(ai, bj, At, Bt) do { __builtin_amdgcn_s_setprio(1); _Pragma("unroll") for (int m = 0; m < 4; ++m) _Pragma("unroll") for (int n = 0; n < 2; ++n) _Pragma("unroll") for (int k = 0; k < 2; ++k) \
;         acc[ai][bj][m][n] = MmaOp<Epi::I8>::run(Bt[n][k], At[m][k], acc[ai][bj][m][n]); __builtin_amdgcn_s_setprio(0); } while (0)
; #define PG8_WAIT_L(n) asm volatile("s_waitcnt lgkmcnt(" #n ")" ::: "memory")
; #define PG8_BAR __builtin_amdgcn_s_barrier()
; #define PG8_SCHED __builtin_amdgcn_sched_barrier(0)
; template <class Epi, class Sched>
; __device__ __forceinline__ void gemm_phase(LAS unsigned char* lds, const Gemm g, const Sched& S, const Epi& E) {
;     ...
;             PG8_LDB(B0, 0, 0); PG8_SCHED; PG8_LDA(At, 0, 0); PG8_STAGE(PG8_SA(1, 1), a1 + hstepA, voffA);
;             PG8_WAIT_L(8); PG8_BAR; PG8_WAIT_L(0); PG8_MMA(0, 0, At, B0); PG8_BAR; PG8_SCHED;
;     ...
;         if (!has_next) break;
; #pragma unroll
;         for (int a = 0; a < 2; ++a)
; #pragma unroll
;             for (int b = 0; b < 2; ++b)
; #pragma unroll
;                 for (int m = 0; m < 4; ++m)
; #pragma unroll
;                     for (int n = 0; n < 2; ++n) acc[a][b][m][n] = (acc_t){0, 0, 0, 0};
;         cur = nxt; cA = nA; cB = nB; ++ui;
.LBB0_864:
	s_ashr_i32 s11, s10, 31
	v_cmp_lt_i64_e32 vcc, s[12:13], v[140:141]
	s_lshl_b64 s[12:13], s[10:11], 20
	v_readlane_b32 s14, v239, 25
	v_readlane_b32 s15, v239, 26
	s_add_u32 s12, s14, s12
	s_addc_u32 s13, s15, s13
	s_and_b64 s[14:15], vcc, exec
	s_cselect_b32 s11, s13, s19
	s_cselect_b32 s40, s12, s18
	s_ashr_i32 s9, s8, 31
	s_lshl_b64 s[14:15], s[8:9], 20
	v_readlane_b32 s22, v239, 23
	v_readlane_b32 s23, v239, 24
	s_add_u32 s14, s22, s14
	s_addc_u32 s15, s23, s15
	s_and_b64 s[22:23], vcc, exec
	s_cselect_b32 s9, s15, s21
	s_cselect_b32 s41, s14, s20
	s_add_u32 s18, s18, 0x80080
	s_addc_u32 s19, s19, 0
	s_add_u32 s42, s20, 0x100
	v_mov_b32_e32 v0, 0
	s_addc_u32 s43, s21, 0
	s_mov_b32 s44, -2
	v_mov_b32_e32 v1, v0
	v_mov_b32_e32 v2, v0
	v_mov_b32_e32 v3, v0
	v_mov_b32_e32 v8, v0
	v_mov_b32_e32 v9, v0
	v_mov_b32_e32 v10, v0
	v_mov_b32_e32 v11, v0
	v_mov_b32_e32 v16, v0
	v_mov_b32_e32 v17, v0
	v_mov_b32_e32 v18, v0
	v_mov_b32_e32 v19, v0
	v_mov_b32_e32 v24, v0
	v_mov_b32_e32 v25, v0
	v_mov_b32_e32 v26, v0
	v_mov_b32_e32 v27, v0
	v_mov_b32_e32 v32, v0
	v_mov_b32_e32 v33, v0
	v_mov_b32_e32 v34, v0
	v_mov_b32_e32 v35, v0
	v_mov_b32_e32 v40, v0
	v_mov_b32_e32 v41, v0
	v_mov_b32_e32 v42, v0
	v_mov_b32_e32 v43, v0
	v_mov_b32_e32 v48, v0
	v_mov_b32_e32 v49, v0
	v_mov_b32_e32 v50, v0
	v_mov_b32_e32 v51, v0
	v_mov_b32_e32 v56, v0
	v_mov_b32_e32 v57, v0
	v_mov_b32_e32 v58, v0
	v_mov_b32_e32 v59, v0
	v_mov_b32_e32 v4, v0
	v_mov_b32_e32 v5, v0
	v_mov_b32_e32 v6, v0
	v_mov_b32_e32 v7, v0
	v_mov_b32_e32 v12, v0
	v_mov_b32_e32 v13, v0
	v_mov_b32_e32 v14, v0
	v_mov_b32_e32 v15, v0
	v_mov_b32_e32 v20, v0
	v_mov_b32_e32 v21, v0
	v_mov_b32_e32 v22, v0
	v_mov_b32_e32 v23, v0
	v_mov_b32_e32 v28, v0
	v_mov_b32_e32 v29, v0
	v_mov_b32_e32 v30, v0
	v_mov_b32_e32 v31, v0
	v_mov_b32_e32 v36, v0
	v_mov_b32_e32 v37, v0
	v_mov_b32_e32 v38, v0
	v_mov_b32_e32 v39, v0
	v_mov_b32_e32 v44, v0
	v_mov_b32_e32 v45, v0
	v_mov_b32_e32 v46, v0
	v_mov_b32_e32 v47, v0
	v_mov_b32_e32 v52, v0
	v_mov_b32_e32 v53, v0
	v_mov_b32_e32 v54, v0
	v_mov_b32_e32 v55, v0
	v_mov_b32_e32 v60, v0
	v_mov_b32_e32 v61, v0
	v_mov_b32_e32 v62, v0
	v_mov_b32_e32 v63, v0
	v_mov_b32_e32 v64, v0
	v_mov_b32_e32 v65, v0
	v_mov_b32_e32 v66, v0
	v_mov_b32_e32 v67, v0
	v_mov_b32_e32 v72, v0
	v_mov_b32_e32 v73, v0
	v_mov_b32_e32 v74, v0
	v_mov_b32_e32 v75, v0
	v_mov_b32_e32 v80, v0
	v_mov_b32_e32 v81, v0
	v_mov_b32_e32 v82, v0
	v_mov_b32_e32 v83, v0
	v_mov_b32_e32 v88, v0
	v_mov_b32_e32 v89, v0
	v_mov_b32_e32 v90, v0
	v_mov_b32_e32 v91, v0
	v_mov_b32_e32 v96, v0
	v_mov_b32_e32 v97, v0
	v_mov_b32_e32 v98, v0
	v_mov_b32_e32 v99, v0
	v_mov_b32_e32 v104, v0
	v_mov_b32_e32 v105, v0
	v_mov_b32_e32 v106, v0
	v_mov_b32_e32 v107, v0
	v_mov_b32_e32 v120, v0
	v_mov_b32_e32 v121, v0
	v_mov_b32_e32 v122, v0
	v_mov_b32_e32 v123, v0
	v_mov_b32_e32 v124, v0
	v_mov_b32_e32 v125, v0
	v_mov_b32_e32 v126, v0
	v_mov_b32_e32 v127, v0
	v_mov_b32_e32 v68, v0
	v_mov_b32_e32 v69, v0
	v_mov_b32_e32 v70, v0
	v_mov_b32_e32 v71, v0
	v_mov_b32_e32 v76, v0
	v_mov_b32_e32 v77, v0
	v_mov_b32_e32 v78, v0
	v_mov_b32_e32 v79, v0
	v_mov_b32_e32 v84, v0
	v_mov_b32_e32 v85, v0
	v_mov_b32_e32 v86, v0
	v_mov_b32_e32 v87, v0
	v_mov_b32_e32 v92, v0
	v_mov_b32_e32 v93, v0
	v_mov_b32_e32 v94, v0
	v_mov_b32_e32 v95, v0
	v_mov_b32_e32 v100, v0
	v_mov_b32_e32 v101, v0
	v_mov_b32_e32 v102, v0
	v_mov_b32_e32 v103, v0
	v_mov_b32_e32 v108, v0
	v_mov_b32_e32 v109, v0
	v_mov_b32_e32 v110, v0
	v_mov_b32_e32 v111, v0
	v_mov_b32_e32 v112, v0
	v_mov_b32_e32 v113, v0
	v_mov_b32_e32 v114, v0
	v_mov_b32_e32 v115, v0
	v_mov_b32_e32 v116, v0
	v_mov_b32_e32 v117, v0
	v_mov_b32_e32 v118, v0
	v_mov_b32_e32 v119, v0
.LBB0_865:
	ds_read_b128 v[154:157], v149
	ds_read_b128 v[158:161], v149 offset:1024
	ds_read_b128 v[162:165], v149 offset:2048
	ds_read_b128 v[166:169], v149 offset:3072
	s_add_u32 s20, s18, 0xfff80080
	s_addc_u32 s21, s19, -1
	s_cmp_eq_u32 s44, 28
	s_cselect_b32 s23, s11, s21
	s_cselect_b32 s22, s40, s20
	s_cselect_b32 s21, s9, s43
	s_cselect_b32 s20, s41, s42
	v_lshl_add_u64 v[144:145], s[18:19], 0, v[136:137]
	s_add_i32 m0, s17, 0xc000
	ds_read_b128 v[170:173], v150
	ds_read_b128 v[178:181], v150 offset:1024
	ds_read_b128 v[182:185], v150 offset:2048
	ds_read_b128 v[186:189], v150 offset:3072
	ds_read_b128 v[190:193], v150 offset:4096
	ds_read_b128 v[194:197], v150 offset:5120
	ds_read_b128 v[198:201], v150 offset:6144
	ds_read_b128 v[202:205], v150 offset:7168
	global_load_lds_dwordx4 v[144:145], off
	v_lshl_add_u64 v[144:145], s[18:19], 0, v[138:139]
	s_add_i32 m0, s17, 0xe000
	s_nop 0
	global_load_lds_dwordx4 v[144:145], off
	s_waitcnt lgkmcnt(8)
	s_barrier
	s_waitcnt lgkmcnt(0)
	s_setprio 1
	s_waitcnt lgkmcnt(0)
	v_mfma_f32_16x16x32_bf16 v[116:119], v[154:157], v[170:173], v[116:119]
	v_mfma_f32_16x16x32_bf16 v[112:115], v[162:165], v[170:173], v[112:115]
	v_mfma_f32_16x16x32_bf16 v[108:111], v[154:157], v[182:185], v[108:111]
	v_mfma_f32_16x16x32_bf16 v[100:103], v[162:165], v[182:185], v[100:103]
	v_mfma_f32_16x16x32_bf16 v[92:95], v[154:157], v[190:193], v[92:95]
	v_mfma_f32_16x16x32_bf16 v[84:87], v[162:165], v[190:193], v[84:87]
	v_mfma_f32_16x16x32_bf16 v[76:79], v[154:157], v[198:201], v[76:79]
	v_mfma_f32_16x16x32_bf16 v[68:71], v[162:165], v[198:201], v[68:71]
	v_mfma_f32_16x16x32_bf16 v[116:119], v[158:161], v[178:181], v[116:119]
	v_mfma_f32_16x16x32_bf16 v[112:115], v[166:169], v[178:181], v[112:115]
	v_mfma_f32_16x16x32_bf16 v[108:111], v[158:161], v[186:189], v[108:111]
	v_mfma_f32_16x16x32_bf16 v[100:103], v[166:169], v[186:189], v[100:103]
	v_mfma_f32_16x16x32_bf16 v[92:95], v[158:161], v[194:197], v[92:95]
	v_mfma_f32_16x16x32_bf16 v[84:87], v[166:169], v[194:197], v[84:87]
	v_mfma_f32_16x16x32_bf16 v[76:79], v[158:161], v[202:205], v[76:79]
	v_mfma_f32_16x16x32_bf16 v[68:71], v[166:169], v[202:205], v[68:71]
	s_setprio 0
	s_barrier
; #define PG8_STAGE(bufoff, gbase, voff) do { _Pragma("unroll") for (int _i = 0; _i < 2; ++_i) \
;         __builtin_amdgcn_global_load_lds((const unsigned*)((const char*)(gbase) + (voff)[_i]), (LAS unsigned*)(lds + (bufoff) + ldsw + _i * 8192), 16, 0, 0); } while (0)
; #define PG8_LDA(dst, b, h) do { _Pragma("unroll") for (int m = 0; m < 4; ++m) _Pragma("unroll") for (int k = 0; k < 2; ++k) dst[m][k] = *(const LAS bf16x8*)(lds + PG8_SA(b, h) + aoff + m * 2048 + k * 1024); } while (0)
; #define PG8_LDB(dst, b, h) do { _Pragma("unroll") for (int n = 0; n < 2; ++n) _Pragma("unroll") for (int k = 0; k < 2; ++k) dst[n][k] = *(const LAS bf16x8*)(lds + PG8_SB(b, h) + boff + n * 2048 + k * 1024); } while (0)
; #define PG8_MMA(ai, bj, At, Bt) do { __builtin_amdgcn_s_setprio(1); _Pragma("unroll") for (int m = 0; m < 4; ++m) _Pragma("unroll") for (int n = 0; n < 2; ++n) _Pragma("unroll") for (int k = 0; k < 2; ++k) \
;         acc[ai][bj][m][n] = MmaOp<Epi::I8>::run(Bt[n][k], At[m][k], acc[ai][bj][m][n]); __builtin_amdgcn_s_setprio(0); } while (0)
; #define PG8_WAIT_V(n) asm volatile("s_waitcnt vmcnt(" #n ")" ::: "memory")
; #define PG8_WAIT_L(n) asm volatile("s_waitcnt lgkmcnt(" #n ")" ::: "memory")
; #define PG8_BAR __builtin_amdgcn_s_barrier()
; #define PG8_SCHED __builtin_amdgcn_sched_barrier(0)
; template <class Epi, class Sched>
; __device__ __forceinline__ void gemm_phase(LAS unsigned char* lds, const Gemm g, const Sched& S, const Epi& E) {
;     ...
;             PG8_LDB(B1, 0, 1); PG8_STAGE(PG8_SB(0, 0), b2, voffB);
;             PG8_BAR; PG8_WAIT_L(0); PG8_MMA(0, 1, At, B1); PG8_BAR;
;             PG8_LDA(At, 0, 1); PG8_STAGE(PG8_SA(0, 0), a2, voffA);
;             PG8_BAR; PG8_WAIT_L(0); PG8_MMA(1, 0, At, B0); PG8_BAR; PG8_SCHED;
;             PG8_STAGE(PG8_SB(0, 1), b2 + hstepB, voffB);
;             PG8_WAIT_V(6); PG8_BAR; PG8_MMA(1, 1, At, B1); PG8_BAR;
;             PG8_LDB(B0, 1, 0); PG8_SCHED; PG8_LDA(At, 1, 0); PG8_STAGE(PG8_SA(0, 1), a2 + hstepA, voffA);
;             PG8_WAIT_L(8); PG8_BAR; PG8_WAIT_L(0); PG8_MMA(0, 0, At, B0); PG8_BAR; PG8_SCHED;
;             PG8_LDB(B1, 1, 1); PG8_STAGE(PG8_SB(1, 0), b3, voffB);
	s_add_i32 s45, s36, s25
	v_lshl_add_u64 v[144:145], s[20:21], 0, v[132:133]
	s_mov_b32 m0, s45
	ds_read_b128 v[206:209], v151
	ds_read_b128 v[210:213], v151 offset:1024
	ds_read_b128 v[214:217], v151 offset:2048
	ds_read_b128 v[218:221], v151 offset:3072
	global_load_lds_dwordx4 v[144:145], off
	v_lshl_add_u64 v[174:175], s[20:21], 0, v[128:129]
	s_add_i32 m0, s45, 0x2000
	s_nop 0
	global_load_lds_dwordx4 v[174:175], off
	s_barrier
	s_waitcnt lgkmcnt(0)
	s_setprio 1
	s_waitcnt lgkmcnt(0)
	v_mfma_f32_16x16x32_bf16 v[124:127], v[206:209], v[170:173], v[124:127]
	v_mfma_f32_16x16x32_bf16 v[120:123], v[214:217], v[170:173], v[120:123]
	v_mfma_f32_16x16x32_bf16 v[104:107], v[206:209], v[182:185], v[104:107]
	v_mfma_f32_16x16x32_bf16 v[96:99], v[214:217], v[182:185], v[96:99]
	v_mfma_f32_16x16x32_bf16 v[88:91], v[206:209], v[190:193], v[88:91]
	v_mfma_f32_16x16x32_bf16 v[80:83], v[214:217], v[190:193], v[80:83]
	v_mfma_f32_16x16x32_bf16 v[72:75], v[206:209], v[198:201], v[72:75]
	v_mfma_f32_16x16x32_bf16 v[64:67], v[214:217], v[198:201], v[64:67]
	v_mfma_f32_16x16x32_bf16 v[124:127], v[210:213], v[178:181], v[124:127]
	v_mfma_f32_16x16x32_bf16 v[120:123], v[218:221], v[178:181], v[120:123]
	v_mfma_f32_16x16x32_bf16 v[104:107], v[210:213], v[186:189], v[104:107]
	v_mfma_f32_16x16x32_bf16 v[96:99], v[218:221], v[186:189], v[96:99]
	v_mfma_f32_16x16x32_bf16 v[88:91], v[210:213], v[194:197], v[88:91]
	v_mfma_f32_16x16x32_bf16 v[80:83], v[218:221], v[194:197], v[80:83]
	v_mfma_f32_16x16x32_bf16 v[72:75], v[210:213], v[202:205], v[72:75]
	v_mfma_f32_16x16x32_bf16 v[64:67], v[218:221], v[202:205], v[64:67]
	s_setprio 0
	s_mov_b32 m0, s17
	v_lshl_add_u64 v[222:223], s[22:23], 0, v[134:135]
	s_barrier
	ds_read_b128 v[170:173], v150 offset:16384
	ds_read_b128 v[178:181], v150 offset:17408
	ds_read_b128 v[182:185], v150 offset:18432
	ds_read_b128 v[186:189], v150 offset:19456
	ds_read_b128 v[190:193], v150 offset:20480
	ds_read_b128 v[194:197], v150 offset:21504
	ds_read_b128 v[198:201], v150 offset:22528
	ds_read_b128 v[202:205], v150 offset:23552
	global_load_lds_dwordx4 v[222:223], off
	v_lshl_add_u64 v[224:225], s[22:23], 0, v[130:131]
	s_mov_b32 m0, s28
	s_nop 0
	global_load_lds_dwordx4 v[224:225], off
	s_barrier
	s_waitcnt lgkmcnt(0)
	s_setprio 1
	s_waitcnt lgkmcnt(0)
	v_mfma_f32_16x16x32_bf16 v[60:63], v[154:157], v[170:173], v[60:63]
	v_mfma_f32_16x16x32_bf16 v[52:55], v[162:165], v[170:173], v[52:55]
	v_mfma_f32_16x16x32_bf16 v[44:47], v[154:157], v[182:185], v[44:47]
	v_mfma_f32_16x16x32_bf16 v[36:39], v[162:165], v[182:185], v[36:39]
	v_mfma_f32_16x16x32_bf16 v[28:31], v[154:157], v[190:193], v[28:31]
	v_mfma_f32_16x16x32_bf16 v[20:23], v[162:165], v[190:193], v[20:23]
	v_mfma_f32_16x16x32_bf16 v[12:15], v[154:157], v[198:201], v[12:15]
	v_mfma_f32_16x16x32_bf16 v[4:7], v[162:165], v[198:201], v[4:7]
	v_mfma_f32_16x16x32_bf16 v[60:63], v[158:161], v[178:181], v[60:63]
	v_mfma_f32_16x16x32_bf16 v[52:55], v[166:169], v[178:181], v[52:55]
	v_mfma_f32_16x16x32_bf16 v[44:47], v[158:161], v[186:189], v[44:47]
	v_mfma_f32_16x16x32_bf16 v[36:39], v[166:169], v[186:189], v[36:39]
	v_mfma_f32_16x16x32_bf16 v[28:31], v[158:161], v[194:197], v[28:31]
	v_mfma_f32_16x16x32_bf16 v[20:23], v[166:169], v[194:197], v[20:23]
	v_mfma_f32_16x16x32_bf16 v[12:15], v[158:161], v[202:205], v[12:15]
	v_mfma_f32_16x16x32_bf16 v[4:7], v[166:169], v[202:205], v[4:7]
	s_setprio 0
	s_barrier
	s_add_u32 s46, s20, 0x80000
	s_addc_u32 s47, s21, 0
	s_add_i32 s45, s37, s25
	v_lshl_add_u64 v[154:155], s[46:47], 0, v[132:133]
	s_mov_b32 m0, s45
	s_nop 0
	global_load_lds_dwordx4 v[154:155], off
	v_lshl_add_u64 v[154:155], s[46:47], 0, v[128:129]
	s_add_i32 m0, s45, 0x2000
	s_nop 0
	global_load_lds_dwordx4 v[154:155], off
	s_waitcnt vmcnt(6)
	s_barrier
	s_setprio 1
	v_mfma_f32_16x16x32_bf16 v[56:59], v[206:209], v[170:173], v[56:59]
	v_mfma_f32_16x16x32_bf16 v[48:51], v[214:217], v[170:173], v[48:51]
	v_mfma_f32_16x16x32_bf16 v[40:43], v[206:209], v[182:185], v[40:43]
	v_mfma_f32_16x16x32_bf16 v[32:35], v[214:217], v[182:185], v[32:35]
	v_mfma_f32_16x16x32_bf16 v[24:27], v[206:209], v[190:193], v[24:27]
	v_mfma_f32_16x16x32_bf16 v[16:19], v[214:217], v[190:193], v[16:19]
	v_mfma_f32_16x16x32_bf16 v[8:11], v[206:209], v[198:201], v[8:11]
	v_mfma_f32_16x16x32_bf16 v[0:3], v[214:217], v[198:201], v[0:3]
	v_mfma_f32_16x16x32_bf16 v[56:59], v[210:213], v[178:181], v[56:59]
	v_mfma_f32_16x16x32_bf16 v[48:51], v[218:221], v[178:181], v[48:51]
	v_mfma_f32_16x16x32_bf16 v[40:43], v[210:213], v[186:189], v[40:43]
	v_mfma_f32_16x16x32_bf16 v[32:35], v[218:221], v[186:189], v[32:35]
	v_mfma_f32_16x16x32_bf16 v[24:27], v[210:213], v[194:197], v[24:27]
	v_mfma_f32_16x16x32_bf16 v[16:19], v[218:221], v[194:197], v[16:19]
	v_mfma_f32_16x16x32_bf16 v[8:11], v[210:213], v[202:205], v[8:11]
	v_mfma_f32_16x16x32_bf16 v[0:3], v[218:221], v[202:205], v[0:3]
	s_setprio 0
	s_add_i32 s45, 0, 0x18000
	v_add_u32_e32 v153, s45, v147
	s_barrier
	ds_read_b128 v[154:157], v153
	ds_read_b128 v[158:161], v153 offset:1024
	ds_read_b128 v[162:165], v153 offset:2048
	ds_read_b128 v[166:169], v153 offset:3072
	s_add_u32 s22, s22, 0x80000
	s_addc_u32 s23, s23, 0
	s_mov_b32 m0, s29
	v_lshl_add_u64 v[206:207], s[22:23], 0, v[134:135]
	ds_read_b128 v[170:173], v150 offset:32768
	ds_read_b128 v[178:181], v150 offset:33792
	ds_read_b128 v[182:185], v150 offset:34816
	ds_read_b128 v[186:189], v150 offset:35840
	ds_read_b128 v[190:193], v150 offset:36864
	ds_read_b128 v[194:197], v150 offset:37888
	ds_read_b128 v[198:201], v150 offset:38912
	ds_read_b128 v[202:205], v150 offset:39936
	global_load_lds_dwordx4 v[206:207], off
	v_lshl_add_u64 v[206:207], s[22:23], 0, v[130:131]
	s_mov_b32 m0, s30
	s_nop 0
	global_load_lds_dwordx4 v[206:207], off
	s_waitcnt lgkmcnt(8)
	s_barrier
; #define PG8_STAGE(bufoff, gbase, voff) do { _Pragma("unroll") for (int _i = 0; _i < 2; ++_i) \
;         __builtin_amdgcn_global_load_lds((const unsigned*)((const char*)(gbase) + (voff)[_i]), (LAS unsigned*)(lds + (bufoff) + ldsw + _i * 8192), 16, 0, 0); } while (0)
; #define PG8_LDA(dst, b, h) do { _Pragma("unroll") for (int m = 0; m < 4; ++m) _Pragma("unroll") for (int k = 0; k < 2; ++k) dst[m][k] = *(const LAS bf16x8*)(lds + PG8_SA(b, h) + aoff + m * 2048 + k * 1024); } while (0)
; #define PG8_LDB(dst, b, h) do { _Pragma("unroll") for (int n = 0; n < 2; ++n) _Pragma("unroll") for (int k = 0; k < 2; ++k) dst[n][k] = *(const LAS bf16x8*)(lds + PG8_SB(b, h) + boff + n * 2048 + k * 1024); } while (0)
; #define PG8_MMA(ai, bj, At, Bt) do { __builtin_amdgcn_s_setprio(1); _Pragma("unroll") for (int m = 0; m < 4; ++m) _Pragma("unroll") for (int n = 0; n < 2; ++n) _Pragma("unroll") for (int k = 0; k < 2; ++k) \
;         acc[ai][bj][m][n] = MmaOp<Epi::I8>::run(Bt[n][k], At[m][k], acc[ai][bj][m][n]); __builtin_amdgcn_s_setprio(0); } while (0)
; #define PG8_WAIT_V(n) asm volatile("s_waitcnt vmcnt(" #n ")" ::: "memory")
; #define PG8_WAIT_L(n) asm volatile("s_waitcnt lgkmcnt(" #n ")" ::: "memory")
; #define PG8_BAR __builtin_amdgcn_s_barrier()
; #define PG8_SCHED __builtin_amdgcn_sched_barrier(0)
; template <class Epi, class Sched>
; __device__ __forceinline__ void gemm_phase(LAS unsigned char* lds, const Gemm g, const Sched& S, const Epi& E) {
;     ...
;             PG8_WAIT_L(8); PG8_BAR; PG8_WAIT_L(0); PG8_MMA(0, 0, At, B0); PG8_BAR; PG8_SCHED;
;             PG8_LDB(B1, 1, 1); PG8_STAGE(PG8_SB(1, 0), b3, voffB);
;             PG8_BAR; PG8_WAIT_L(0); PG8_MMA(0, 1, At, B1); PG8_BAR;
;             PG8_LDA(At, 1, 1); PG8_STAGE(PG8_SA(1, 0), a3, voffA);
;             PG8_BAR; PG8_WAIT_L(0); PG8_MMA(1, 0, At, B0); PG8_BAR; PG8_SCHED;
;             PG8_STAGE(PG8_SB(1, 1), b3 + hstepB, voffB);
;             PG8_WAIT_V(6); PG8_BAR; PG8_MMA(1, 1, At, B1); PG8_BAR;
	s_waitcnt lgkmcnt(0)
	s_setprio 1
	s_waitcnt lgkmcnt(0)
	v_mfma_f32_16x16x32_bf16 v[116:119], v[154:157], v[170:173], v[116:119]
	v_mfma_f32_16x16x32_bf16 v[112:115], v[162:165], v[170:173], v[112:115]
	v_mfma_f32_16x16x32_bf16 v[108:111], v[154:157], v[182:185], v[108:111]
	v_mfma_f32_16x16x32_bf16 v[100:103], v[162:165], v[182:185], v[100:103]
	v_mfma_f32_16x16x32_bf16 v[92:95], v[154:157], v[190:193], v[92:95]
	v_mfma_f32_16x16x32_bf16 v[84:87], v[162:165], v[190:193], v[84:87]
	v_mfma_f32_16x16x32_bf16 v[76:79], v[154:157], v[198:201], v[76:79]
	v_mfma_f32_16x16x32_bf16 v[68:71], v[162:165], v[198:201], v[68:71]
	v_mfma_f32_16x16x32_bf16 v[116:119], v[158:161], v[178:181], v[116:119]
	v_mfma_f32_16x16x32_bf16 v[112:115], v[166:169], v[178:181], v[112:115]
	v_mfma_f32_16x16x32_bf16 v[108:111], v[158:161], v[186:189], v[108:111]
	v_mfma_f32_16x16x32_bf16 v[100:103], v[166:169], v[186:189], v[100:103]
	v_mfma_f32_16x16x32_bf16 v[92:95], v[158:161], v[194:197], v[92:95]
	v_mfma_f32_16x16x32_bf16 v[84:87], v[166:169], v[194:197], v[84:87]
	v_mfma_f32_16x16x32_bf16 v[76:79], v[158:161], v[202:205], v[76:79]
	v_mfma_f32_16x16x32_bf16 v[68:71], v[166:169], v[202:205], v[68:71]
	s_setprio 0
	s_barrier
	s_add_i32 s22, 0, 0x1c000
	s_add_i32 s23, s45, s25
	v_add_u32_e32 v153, s22, v147
	v_lshl_add_u64 v[144:145], v[144:145], 0, s[6:7]
	s_mov_b32 m0, s23
	ds_read_b128 v[206:209], v153
	ds_read_b128 v[210:213], v153 offset:1024
	ds_read_b128 v[214:217], v153 offset:2048
	ds_read_b128 v[218:221], v153 offset:3072
	global_load_lds_dwordx4 v[144:145], off
	v_lshl_add_u64 v[144:145], v[174:175], 0, s[6:7]
	s_add_i32 m0, s23, 0x2000
	s_nop 0
	global_load_lds_dwordx4 v[144:145], off
	s_barrier
	s_waitcnt lgkmcnt(0)
	s_setprio 1
	s_waitcnt lgkmcnt(0)
	v_mfma_f32_16x16x32_bf16 v[124:127], v[206:209], v[170:173], v[124:127]
	v_mfma_f32_16x16x32_bf16 v[120:123], v[214:217], v[170:173], v[120:123]
	v_mfma_f32_16x16x32_bf16 v[104:107], v[206:209], v[182:185], v[104:107]
	v_mfma_f32_16x16x32_bf16 v[96:99], v[214:217], v[182:185], v[96:99]
	v_mfma_f32_16x16x32_bf16 v[88:91], v[206:209], v[190:193], v[88:91]
	v_mfma_f32_16x16x32_bf16 v[80:83], v[214:217], v[190:193], v[80:83]
	v_mfma_f32_16x16x32_bf16 v[72:75], v[206:209], v[198:201], v[72:75]
	v_mfma_f32_16x16x32_bf16 v[64:67], v[214:217], v[198:201], v[64:67]
	v_mfma_f32_16x16x32_bf16 v[124:127], v[210:213], v[178:181], v[124:127]
	v_mfma_f32_16x16x32_bf16 v[120:123], v[218:221], v[178:181], v[120:123]
	v_mfma_f32_16x16x32_bf16 v[104:107], v[210:213], v[186:189], v[104:107]
	v_mfma_f32_16x16x32_bf16 v[96:99], v[218:221], v[186:189], v[96:99]
	v_mfma_f32_16x16x32_bf16 v[88:91], v[210:213], v[194:197], v[88:91]
	v_mfma_f32_16x16x32_bf16 v[80:83], v[218:221], v[194:197], v[80:83]
	v_mfma_f32_16x16x32_bf16 v[72:75], v[210:213], v[202:205], v[72:75]
	v_mfma_f32_16x16x32_bf16 v[64:67], v[218:221], v[202:205], v[64:67]
	s_setprio 0
	s_mov_b32 m0, s33
	v_lshl_add_u64 v[144:145], v[222:223], 0, s[6:7]
	s_barrier
	ds_read_b128 v[170:173], v150 offset:49152
	ds_read_b128 v[178:181], v150 offset:50176
	ds_read_b128 v[182:185], v150 offset:51200
	ds_read_b128 v[186:189], v150 offset:52224
	ds_read_b128 v[190:193], v150 offset:53248
	ds_read_b128 v[194:197], v150 offset:54272
	ds_read_b128 v[198:201], v150 offset:55296
	ds_read_b128 v[202:205], v150 offset:56320
	global_load_lds_dwordx4 v[144:145], off
	v_lshl_add_u64 v[144:145], v[224:225], 0, s[6:7]
	s_mov_b32 m0, s34
	s_nop 0
	global_load_lds_dwordx4 v[144:145], off
	s_barrier
	s_waitcnt lgkmcnt(0)
	s_setprio 1
	s_waitcnt lgkmcnt(0)
	v_mfma_f32_16x16x32_bf16 v[60:63], v[154:157], v[170:173], v[60:63]
	v_mfma_f32_16x16x32_bf16 v[52:55], v[162:165], v[170:173], v[52:55]
	v_mfma_f32_16x16x32_bf16 v[44:47], v[154:157], v[182:185], v[44:47]
	v_mfma_f32_16x16x32_bf16 v[36:39], v[162:165], v[182:185], v[36:39]
	v_mfma_f32_16x16x32_bf16 v[28:31], v[154:157], v[190:193], v[28:31]
	v_mfma_f32_16x16x32_bf16 v[20:23], v[162:165], v[190:193], v[20:23]
	v_mfma_f32_16x16x32_bf16 v[12:15], v[154:157], v[198:201], v[12:15]
	v_mfma_f32_16x16x32_bf16 v[4:7], v[162:165], v[198:201], v[4:7]
	v_mfma_f32_16x16x32_bf16 v[60:63], v[158:161], v[178:181], v[60:63]
	v_mfma_f32_16x16x32_bf16 v[52:55], v[166:169], v[178:181], v[52:55]
	v_mfma_f32_16x16x32_bf16 v[44:47], v[158:161], v[186:189], v[44:47]
	v_mfma_f32_16x16x32_bf16 v[36:39], v[166:169], v[186:189], v[36:39]
	v_mfma_f32_16x16x32_bf16 v[28:31], v[158:161], v[194:197], v[28:31]
	v_mfma_f32_16x16x32_bf16 v[20:23], v[166:169], v[194:197], v[20:23]
	v_mfma_f32_16x16x32_bf16 v[12:15], v[158:161], v[202:205], v[12:15]
	v_mfma_f32_16x16x32_bf16 v[4:7], v[166:169], v[202:205], v[4:7]
	s_setprio 0
	s_barrier
	s_add_u32 s20, s20, 0x80080
	s_addc_u32 s21, s21, 0
	s_add_i32 s22, s22, s25
	v_lshl_add_u64 v[144:145], s[20:21], 0, v[132:133]
	s_mov_b32 m0, s22
	s_nop 0
	global_load_lds_dwordx4 v[144:145], off
	v_lshl_add_u64 v[144:145], s[20:21], 0, v[128:129]
	s_add_i32 m0, s22, 0x2000
	s_nop 0
	global_load_lds_dwordx4 v[144:145], off
	s_waitcnt vmcnt(6)
	s_barrier
; __device__ __forceinline__ unsigned cvt_pk_bf16(float lo, float hi) { unsigned r; asm volatile("v_cvt_pk_bf16_f32 %0, %1, %2" : "=v"(r) : "v"(lo), "v"(hi)); return r; }
; __device__ __forceinline__ float ld_agent(const float* p) { return __hip_atomic_load(p, __ATOMIC_RELAXED, __HIP_MEMORY_SCOPE_AGENT); }
; __device__ __forceinline__ float sigm(float x) { return __builtin_amdgcn_rcpf(1.f + __builtin_amdgcn_exp2f(-LOG2E * x)); }
; #define PG8_MMA(ai, bj, At, Bt) do { __builtin_amdgcn_s_setprio(1); _Pragma("unroll") for (int m = 0; m < 4; ++m) _Pragma("unroll") for (int n = 0; n < 2; ++n) _Pragma("unroll") for (int k = 0; k < 2; ++k) \
;         acc[ai][bj][m][n] = MmaOp<Epi::I8>::run(Bt[n][k], At[m][k], acc[ai][bj][m][n]); __builtin_amdgcn_s_setprio(0); } while (0)
; #define PG8_WAIT_V(n) asm volatile("s_waitcnt vmcnt(" #n ")" ::: "memory")
; #define PG8_BAR __builtin_amdgcn_s_barrier()
;     __device__ __forceinline__ void operator()(const f32x4 (&acc)[2][2][4][2], const Unit& u, int wr, int wc, int fr, int fq) const {
;         const int row0 = u.pm * BM + wr * 64 + fr, col0 = u.pn * HALF + wc * 32 + 8 * fq;
;         float sq[8];
; #pragma unroll
;         for (int g = 0; g < 8; ++g) sq[g] = ld_agent(ssq + row0 + (g >> 2) * HALF + (g & 3) * 16);
; #pragma unroll
;         for (int ai = 0; ai < 2; ++ai)
; #pragma unroll
;             for (int m = 0; m < 4; ++m) {
;                 const int r = row0 + ai * HALF + m * 16; const float rs = __builtin_amdgcn_rsqf(sq[ai * 4 + m] * (1.f / 2048.f) + EPS);
;                 float v[8];
; #pragma unroll
;                 for (int n = 0; n < 2; ++n)
; #pragma unroll
;                     for (int j = 0; j < 4; ++j) { const float g = acc[ai][0][m][n][j] * rs, up = acc[ai][1][m][n][j] * rs; v[n * 4 + j] = g * sigm(g) * up; }
;                 u32x4 w; w.x = cvt_pk_bf16(v[0], v[1]); w.y = cvt_pk_bf16(v[2], v[3]); w.z = cvt_pk_bf16(v[4], v[5]); w.w = cvt_pk_bf16(v[6], v[7]);
;                 *(u32x4*)(O + (size_t)r * FF + col0) = w;
;             }
; template <class Epi, class Sched>
; __device__ __forceinline__ void gemm_phase(LAS unsigned char* lds, const Gemm g, const Sched& S, const Epi& E) {
;     ...
;             PG8_WAIT_V(6); PG8_BAR; PG8_MMA(1, 1, At, B1); PG8_BAR;
	s_setprio 1
	v_mfma_f32_16x16x32_bf16 v[56:59], v[206:209], v[170:173], v[56:59]
	v_mfma_f32_16x16x32_bf16 v[48:51], v[214:217], v[170:173], v[48:51]
	v_mfma_f32_16x16x32_bf16 v[40:43], v[206:209], v[182:185], v[40:43]
	v_mfma_f32_16x16x32_bf16 v[32:35], v[214:217], v[182:185], v[32:35]
	v_mfma_f32_16x16x32_bf16 v[24:27], v[206:209], v[190:193], v[24:27]
	v_mfma_f32_16x16x32_bf16 v[16:19], v[214:217], v[190:193], v[16:19]
	v_mfma_f32_16x16x32_bf16 v[8:11], v[206:209], v[198:201], v[8:11]
	v_mfma_f32_16x16x32_bf16 v[0:3], v[214:217], v[198:201], v[0:3]
	v_mfma_f32_16x16x32_bf16 v[56:59], v[210:213], v[178:181], v[56:59]
	v_mfma_f32_16x16x32_bf16 v[48:51], v[218:221], v[178:181], v[48:51]
	v_mfma_f32_16x16x32_bf16 v[40:43], v[210:213], v[186:189], v[40:43]
	v_mfma_f32_16x16x32_bf16 v[32:35], v[218:221], v[186:189], v[32:35]
	v_mfma_f32_16x16x32_bf16 v[24:27], v[210:213], v[194:197], v[24:27]
	v_mfma_f32_16x16x32_bf16 v[16:19], v[218:221], v[194:197], v[16:19]
	v_mfma_f32_16x16x32_bf16 v[8:11], v[210:213], v[202:205], v[8:11]
	v_mfma_f32_16x16x32_bf16 v[0:3], v[218:221], v[202:205], v[0:3]
	s_setprio 0
	s_add_i32 s44, s44, 2
	s_add_u32 s18, s18, 0x100
	s_addc_u32 s19, s19, 0
	s_add_u32 s42, s42, 0x100
	s_addc_u32 s43, s43, 0
	s_cmp_gt_u32 s44, 29
	s_barrier
	s_cbranch_scc0 .LBB0_865
	v_lshl_add_u32 v144, s16, 8, v146
	v_ashrrev_i32_e32 v145, 31, v144
	v_lshl_add_u64 v[154:155], v[144:145], 2, s[2:3]
	global_load_dword v145, v[154:155], off sc1
	global_load_dword v153, v[154:155], off offset:64 sc1
	v_mov_b32_e32 v158, v124
	v_mov_b32_e32 v159, v116
	v_mov_b32_e32 v116, v125
	v_mov_b32_e32 v163, v114
	v_mov_b32_e32 v114, v123
	global_load_dword v125, v[154:155], off offset:128 sc1
	global_load_dword v168, v[154:155], off offset:192 sc1
	global_load_dword v169, v[154:155], off offset:512 sc1
	global_load_dword v124, v[154:155], off offset:576 sc1
	global_load_dword v123, v[154:155], off offset:640 sc1
	global_load_dword v190, v[154:155], off offset:704 sc1
	v_lshl_or_b32 v156, s39, 7, v148
	v_mov_b32_e32 v162, v122
	v_ashrrev_i32_e32 v157, 31, v156
	v_mov_b32_e32 v164, v104
	v_mov_b32_e32 v165, v108
	v_mov_b32_e32 v108, v105
	v_lshlrev_b64 v[104:105], 1, v[156:157]
	v_mov_b32_e32 v161, v118
	v_mov_b32_e32 v118, v127
	v_mov_b32_e32 v160, v126
	v_mov_b32_e32 v126, v120
	v_mov_b32_e32 v127, v112
	v_mov_b32_e32 v112, v121
	v_mov_b64_e32 v[120:121], s[54:55]
	v_mad_i64_i32 v[166:167], s[18:19], v144, s38, v[120:121]
	s_and_b64 vcc, exec, s[0:1]
	s_mov_b32 s39, s8
	s_mov_b32 s16, s10
	s_mov_b64 s[20:21], s[14:15]
	s_waitcnt vmcnt(0)
	v_fmamk_f32 v122, v145, 0x3a000000, v152
	v_rsq_f32_e32 v156, v122
	v_fmamk_f32 v145, v153, 0x3a000000, v152
	v_rsq_f32_e32 v154, v145
	v_pk_mul_f32 v[118:119], v[118:119], v[156:157] op_sel_hi:[1,0]
	v_pk_mul_f32 v[158:159], v[158:159], v[156:157] op_sel_hi:[1,0]
	v_pk_mul_f32 v[116:117], v[116:117], v[156:157] op_sel_hi:[1,0]
	v_pk_mul_f32 v[160:161], v[160:161], v[156:157] op_sel_hi:[1,0]
	v_pk_mul_f32 v[126:127], v[126:127], v[156:157] op_sel_hi:[1,0]
	v_pk_mul_f32 v[112:113], v[112:113], v[156:157] op_sel_hi:[1,0]
	v_pk_mul_f32 v[162:163], v[162:163], v[156:157] op_sel_hi:[1,0]
	v_pk_mul_f32 v[114:115], v[114:115], v[156:157] op_sel_hi:[1,0]
	v_pk_mul_f32 v[156:157], v[164:165], v[154:155] op_sel_hi:[1,0]
	v_mul_f32_e32 v164, 0xbfb8aa3b, v119
	v_pk_mul_f32 v[108:109], v[108:109], v[154:155] op_sel_hi:[1,0]
	v_mul_f32_e32 v145, 0xbfb8aa3b, v159
	v_mul_f32_e32 v153, 0xbfb8aa3b, v117
	v_mul_f32_e32 v155, 0xbfb8aa3b, v161
	v_mul_f32_e32 v165, 0xbfb8aa3b, v127
	v_mul_f32_e32 v170, 0xbfb8aa3b, v113
	v_exp_f32_e32 v164, v164
	v_exp_f32_e32 v145, v145
	v_exp_f32_e32 v153, v153
	v_exp_f32_e32 v155, v155
	v_exp_f32_e32 v165, v165
	v_exp_f32_e32 v170, v170
	v_mul_f32_e32 v172, 0xbfb8aa3b, v115
	v_add_f32_e32 v164, 1.0, v164
	v_mul_f32_e32 v171, 0xbfb8aa3b, v163
	v_exp_f32_e32 v172, v172
	v_add_f32_e32 v145, 1.0, v145
	v_add_f32_e32 v153, 1.0, v153
	v_add_f32_e32 v155, 1.0, v155
	v_add_f32_e32 v165, 1.0, v165
	v_add_f32_e32 v170, 1.0, v170
	v_rcp_f32_e32 v164, v164
	v_mul_f32_e32 v173, 0xbfb8aa3b, v157
	v_exp_f32_e32 v171, v171
	v_rcp_f32_e32 v145, v145
	v_rcp_f32_e32 v153, v153
	v_rcp_f32_e32 v155, v155
	v_rcp_f32_e32 v165, v165
	v_rcp_f32_e32 v170, v170
	v_exp_f32_e32 v173, v173
	v_add_f32_e32 v172, 1.0, v172
	v_mul_f32_e32 v119, v119, v164
	v_add_f32_e32 v171, 1.0, v171
	v_rcp_f32_e32 v172, v172
	v_mul_f32_e32 v145, v159, v145
	v_mul_f32_e32 v117, v117, v153
	v_mul_f32_e32 v153, v161, v155
	v_mul_f32_e32 v127, v127, v165
	v_mul_f32_e32 v113, v113, v170
	v_mul_f32_e32 v118, v118, v119
	v_rcp_f32_e32 v171, v171
	v_mul_f32_e32 v145, v158, v145
	v_mul_f32_e32 v116, v116, v117
	v_mul_f32_e32 v117, v160, v153
	v_mul_f32_e32 v119, v126, v127
	v_mul_f32_e32 v126, v112, v113
	v_cvt_pk_bf16_f32 v112, v145, v116
	v_cvt_pk_bf16_f32 v113, v117, v118
	v_add_f32_e32 v118, 1.0, v173
	v_rcp_f32_e32 v118, v118
	v_mul_f32_e32 v174, 0xbfb8aa3b, v109
	v_mul_f32_e32 v115, v115, v172
	v_exp_f32_e32 v174, v174
	v_mul_f32_e32 v155, v163, v171
	v_mul_f32_e32 v115, v114, v115
	v_lshl_add_u64 v[116:117], v[166:167], 0, v[104:105]
	v_mul_f32_e32 v127, v162, v155
	v_cvt_pk_bf16_f32 v114, v119, v126
	v_cvt_pk_bf16_f32 v115, v127, v115
	global_store_dwordx4 v[116:117], v[112:115], off
	v_add_f32_e32 v119, 1.0, v174
	v_rcp_f32_e32 v119, v119
	v_mul_f32_e32 v112, v157, v118
	v_mul_f32_e32 v114, v156, v112
	v_mov_b32_e32 v112, v106
	v_mov_b32_e32 v113, v110
	v_pk_mul_f32 v[112:113], v[112:113], v[154:155] op_sel_hi:[1,0]
	v_mov_b32_e32 v110, v107
	v_mul_f32_e32 v106, 0xbfb8aa3b, v113
	v_exp_f32_e32 v115, v106
	v_pk_mul_f32 v[106:107], v[110:111], v[154:155] op_sel_hi:[1,0]
; __device__ __forceinline__ unsigned cvt_pk_bf16(float lo, float hi) { unsigned r; asm volatile("v_cvt_pk_bf16_f32 %0, %1, %2" : "=v"(r) : "v"(lo), "v"(hi)); return r; }
; __device__ __forceinline__ float sigm(float x) { return __builtin_amdgcn_rcpf(1.f + __builtin_amdgcn_exp2f(-LOG2E * x)); }
;     __device__ __forceinline__ void operator()(const f32x4 (&acc)[2][2][4][2], const Unit& u, int wr, int wc, int fr, int fq) const {
;     ...
;         for (int ai = 0; ai < 2; ++ai)
; #pragma unroll
;             for (int m = 0; m < 4; ++m) {
;                 const int r = row0 + ai * HALF + m * 16; const float rs = __builtin_amdgcn_rsqf(sq[ai * 4 + m] * (1.f / 2048.f) + EPS);
;                 float v[8];
; #pragma unroll
;                 for (int n = 0; n < 2; ++n)
; #pragma unroll
;                     for (int j = 0; j < 4; ++j) { const float g = acc[ai][0][m][n][j] * rs, up = acc[ai][1][m][n][j] * rs; v[n * 4 + j] = g * sigm(g) * up; }
;                 u32x4 w; w.x = cvt_pk_bf16(v[0], v[1]); w.y = cvt_pk_bf16(v[2], v[3]); w.z = cvt_pk_bf16(v[4], v[5]); w.w = cvt_pk_bf16(v[6], v[7]);
;                 *(u32x4*)(O + (size_t)r * FF + col0) = w;
;             }
	v_mul_f32_e32 v109, v109, v119
	v_mul_f32_e32 v110, 0xbfb8aa3b, v107
	v_exp_f32_e32 v110, v110
	v_mul_f32_e32 v111, v108, v109
	v_add_f32_e32 v108, 1.0, v115
	v_rcp_f32_e32 v115, v108
	v_add_f32_e32 v108, 1.0, v110
	v_rcp_f32_e32 v110, v108
	v_mov_b32_e32 v108, v96
	v_mov_b32_e32 v109, v100
	v_pk_mul_f32 v[108:109], v[108:109], v[154:155] op_sel_hi:[1,0]
	v_mul_f32_e32 v100, v113, v115
	v_mul_f32_e32 v96, 0xbfb8aa3b, v109
	v_exp_f32_e32 v96, v96
	v_mul_f32_e32 v112, v112, v100
	v_mov_b32_e32 v100, v97
	v_mul_f32_e32 v107, v107, v110
	v_add_f32_e32 v96, 1.0, v96
	v_rcp_f32_e32 v110, v96
	v_pk_mul_f32 v[96:97], v[100:101], v[154:155] op_sel_hi:[1,0]
	v_mul_f32_e32 v106, v106, v107
	v_mul_f32_e32 v100, 0xbfb8aa3b, v97
	v_exp_f32_e32 v100, v100
	v_mul_f32_e32 v101, v109, v110
	v_mul_f32_e32 v107, v108, v101
	v_mov_b32_e32 v101, v102
	v_add_f32_e32 v100, 1.0, v100
	v_rcp_f32_e32 v108, v100
	v_mov_b32_e32 v100, v98
	v_pk_mul_f32 v[100:101], v[100:101], v[154:155] op_sel_hi:[1,0]
	v_mov_b32_e32 v102, v99
	v_mul_f32_e32 v98, 0xbfb8aa3b, v101
	v_exp_f32_e32 v109, v98
	v_pk_mul_f32 v[98:99], v[102:103], v[154:155] op_sel_hi:[1,0]
	v_mul_f32_e32 v97, v97, v108
	v_mul_f32_e32 v102, 0xbfb8aa3b, v99
	v_exp_f32_e32 v102, v102
	v_add_f32_e32 v103, 1.0, v109
	v_rcp_f32_e32 v103, v103
	v_mul_f32_e32 v108, v96, v97
	v_add_f32_e32 v102, 1.0, v102
	v_rcp_f32_e32 v102, v102
	v_mul_f32_e32 v96, v101, v103
	v_mul_f32_e32 v100, v100, v96
	v_or_b32_e32 v101, 16, v144
	v_mul_f32_e32 v96, v99, v102
	v_mul_f32_e32 v99, v98, v96
	v_cvt_pk_bf16_f32 v96, v114, v111
	v_cvt_pk_bf16_f32 v97, v112, v106
	v_cvt_pk_bf16_f32 v98, v107, v108
	v_cvt_pk_bf16_f32 v99, v100, v99
	v_fmamk_f32 v100, v125, 0x3a000000, v152
	v_rsq_f32_e32 v100, v100
	v_mov_b32_e32 v106, v88
	v_mov_b32_e32 v107, v92
	v_mad_i64_i32 v[102:103], s[18:19], v101, s38, v[120:121]
	v_pk_mul_f32 v[106:107], v[106:107], v[100:101] op_sel_hi:[1,0]
	v_mov_b32_e32 v92, v89
	v_mul_f32_e32 v88, 0xbfb8aa3b, v107
	v_exp_f32_e32 v101, v88
	s_nop 0
	v_pk_mul_f32 v[88:89], v[92:93], v[100:101] op_sel_hi:[1,0]
	v_add_f32_e32 v101, 1.0, v101
	v_rcp_f32_e32 v101, v101
	v_mul_f32_e32 v92, 0xbfb8aa3b, v89
	v_exp_f32_e32 v108, v92
	v_lshl_add_u64 v[92:93], v[102:103], 0, v[104:105]
	global_store_dwordx4 v[92:93], v[96:99], off
	v_mul_f32_e32 v92, v107, v101
	v_mov_b32_e32 v93, v94
	v_mul_f32_e32 v96, v106, v92
	v_mov_b32_e32 v92, v90
	v_pk_mul_f32 v[92:93], v[92:93], v[100:101] op_sel_hi:[1,0]
	v_add_f32_e32 v102, 1.0, v108
	v_mul_f32_e32 v90, 0xbfb8aa3b, v93
	v_mov_b32_e32 v94, v91
	v_rcp_f32_e32 v102, v102
	v_exp_f32_e32 v97, v90
	v_pk_mul_f32 v[90:91], v[94:95], v[100:101] op_sel_hi:[1,0]
	v_mul_f32_e32 v89, v89, v102
	v_mul_f32_e32 v94, 0xbfb8aa3b, v91
	v_exp_f32_e32 v94, v94
	v_mul_f32_e32 v95, v88, v89
	v_add_f32_e32 v88, 1.0, v97
	v_rcp_f32_e32 v97, v88
	v_add_f32_e32 v88, 1.0, v94
	v_rcp_f32_e32 v94, v88
	v_mov_b32_e32 v88, v80
	v_mov_b32_e32 v89, v84
	v_pk_mul_f32 v[88:89], v[88:89], v[100:101] op_sel_hi:[1,0]
	v_mul_f32_e32 v84, v93, v97
	v_mul_f32_e32 v80, 0xbfb8aa3b, v89
	v_exp_f32_e32 v80, v80
	v_mul_f32_e32 v92, v92, v84
	v_mov_b32_e32 v84, v81
	v_mul_f32_e32 v91, v91, v94
	v_add_f32_e32 v80, 1.0, v80
	v_rcp_f32_e32 v93, v80
	v_pk_mul_f32 v[80:81], v[84:85], v[100:101] op_sel_hi:[1,0]
	v_mul_f32_e32 v90, v90, v91
	v_mul_f32_e32 v84, 0xbfb8aa3b, v81
	v_exp_f32_e32 v84, v84
	v_mul_f32_e32 v85, v89, v93
	v_mul_f32_e32 v88, v88, v85
	v_mov_b32_e32 v85, v86
	v_add_f32_e32 v84, 1.0, v84
	v_rcp_f32_e32 v89, v84
	v_mov_b32_e32 v84, v82
	v_pk_mul_f32 v[84:85], v[84:85], v[100:101] op_sel_hi:[1,0]
	v_mov_b32_e32 v86, v83
	v_mul_f32_e32 v82, 0xbfb8aa3b, v85
	v_exp_f32_e32 v91, v82
	v_pk_mul_f32 v[82:83], v[86:87], v[100:101] op_sel_hi:[1,0]
	v_mul_f32_e32 v81, v81, v89
	v_mul_f32_e32 v86, 0xbfb8aa3b, v83
	v_exp_f32_e32 v86, v86
	v_add_f32_e32 v87, 1.0, v91
	v_rcp_f32_e32 v87, v87
	v_mul_f32_e32 v89, v80, v81
	v_add_f32_e32 v86, 1.0, v86
	v_rcp_f32_e32 v86, v86
	v_mul_f32_e32 v80, v85, v87
	v_mul_f32_e32 v84, v84, v80
	v_or_b32_e32 v85, 32, v144
	v_mul_f32_e32 v80, v83, v86
	v_mul_f32_e32 v83, v82, v80
	v_cvt_pk_bf16_f32 v80, v96, v95
	v_cvt_pk_bf16_f32 v81, v92, v90
	v_cvt_pk_bf16_f32 v82, v88, v89
	v_cvt_pk_bf16_f32 v83, v84, v83
	v_fmamk_f32 v84, v168, 0x3a000000, v152
	v_rsq_f32_e32 v84, v84
	v_mov_b32_e32 v88, v72
	v_mov_b32_e32 v89, v76
	v_mad_i64_i32 v[86:87], s[18:19], v85, s38, v[120:121]
	v_pk_mul_f32 v[88:89], v[88:89], v[84:85] op_sel_hi:[1,0]
	v_mov_b32_e32 v76, v73
	v_mul_f32_e32 v72, 0xbfb8aa3b, v89
	v_exp_f32_e32 v85, v72
	s_nop 0
	v_pk_mul_f32 v[72:73], v[76:77], v[84:85] op_sel_hi:[1,0]
	v_add_f32_e32 v85, 1.0, v85
	v_rcp_f32_e32 v85, v85
	v_mul_f32_e32 v76, 0xbfb8aa3b, v73
	v_exp_f32_e32 v90, v76
	v_lshl_add_u64 v[76:77], v[86:87], 0, v[104:105]
	global_store_dwordx4 v[76:77], v[80:83], off
	v_mul_f32_e32 v76, v89, v85
	v_mov_b32_e32 v77, v78
	v_mul_f32_e32 v80, v88, v76
	v_mov_b32_e32 v76, v74
	v_pk_mul_f32 v[76:77], v[76:77], v[84:85] op_sel_hi:[1,0]
	v_add_f32_e32 v86, 1.0, v90
	v_mul_f32_e32 v74, 0xbfb8aa3b, v77
	v_mov_b32_e32 v78, v75
	v_rcp_f32_e32 v86, v86
	v_exp_f32_e32 v81, v74
	v_pk_mul_f32 v[74:75], v[78:79], v[84:85] op_sel_hi:[1,0]
	v_mul_f32_e32 v73, v73, v86
	v_mul_f32_e32 v78, 0xbfb8aa3b, v75
	v_exp_f32_e32 v78, v78
	v_mul_f32_e32 v79, v72, v73
	v_add_f32_e32 v72, 1.0, v81
	v_rcp_f32_e32 v81, v72
	v_add_f32_e32 v72, 1.0, v78
	v_rcp_f32_e32 v78, v72
	v_mov_b32_e32 v72, v64
	v_mov_b32_e32 v73, v68
	v_pk_mul_f32 v[72:73], v[72:73], v[84:85] op_sel_hi:[1,0]
	v_mul_f32_e32 v68, v77, v81
	v_mul_f32_e32 v64, 0xbfb8aa3b, v73
	v_exp_f32_e32 v64, v64
	v_mul_f32_e32 v76, v76, v68
	v_mov_b32_e32 v68, v65
; __device__ __forceinline__ unsigned cvt_pk_bf16(float lo, float hi) { unsigned r; asm volatile("v_cvt_pk_bf16_f32 %0, %1, %2" : "=v"(r) : "v"(lo), "v"(hi)); return r; }
; __device__ __forceinline__ float sigm(float x) { return __builtin_amdgcn_rcpf(1.f + __builtin_amdgcn_exp2f(-LOG2E * x)); }
;     __device__ __forceinline__ void operator()(const f32x4 (&acc)[2][2][4][2], const Unit& u, int wr, int wc, int fr, int fq) const {
;     ...
;         for (int ai = 0; ai < 2; ++ai)
; #pragma unroll
;             for (int m = 0; m < 4; ++m) {
;                 const int r = row0 + ai * HALF + m * 16; const float rs = __builtin_amdgcn_rsqf(sq[ai * 4 + m] * (1.f / 2048.f) + EPS);
;                 float v[8];
; #pragma unroll
;                 for (int n = 0; n < 2; ++n)
; #pragma unroll
;                     for (int j = 0; j < 4; ++j) { const float g = acc[ai][0][m][n][j] * rs, up = acc[ai][1][m][n][j] * rs; v[n * 4 + j] = g * sigm(g) * up; }
;                 u32x4 w; w.x = cvt_pk_bf16(v[0], v[1]); w.y = cvt_pk_bf16(v[2], v[3]); w.z = cvt_pk_bf16(v[4], v[5]); w.w = cvt_pk_bf16(v[6], v[7]);
;                 *(u32x4*)(O + (size_t)r * FF + col0) = w;
;             }
	v_mul_f32_e32 v75, v75, v78
	v_add_f32_e32 v64, 1.0, v64
	v_rcp_f32_e32 v77, v64
	v_pk_mul_f32 v[64:65], v[68:69], v[84:85] op_sel_hi:[1,0]
	v_mul_f32_e32 v74, v74, v75
	v_mul_f32_e32 v68, 0xbfb8aa3b, v65
	v_exp_f32_e32 v68, v68
	v_mul_f32_e32 v69, v73, v77
	v_mul_f32_e32 v72, v72, v69
	v_mov_b32_e32 v69, v70
	v_add_f32_e32 v68, 1.0, v68
	v_rcp_f32_e32 v73, v68
	v_mov_b32_e32 v68, v66
	v_pk_mul_f32 v[68:69], v[68:69], v[84:85] op_sel_hi:[1,0]
	v_mov_b32_e32 v70, v67
	v_mul_f32_e32 v66, 0xbfb8aa3b, v69
	v_exp_f32_e32 v75, v66
	v_pk_mul_f32 v[66:67], v[70:71], v[84:85] op_sel_hi:[1,0]
	v_mul_f32_e32 v65, v65, v73
	v_mul_f32_e32 v70, 0xbfb8aa3b, v67
	v_exp_f32_e32 v70, v70
	v_add_f32_e32 v71, 1.0, v75
	v_rcp_f32_e32 v71, v71
	v_mul_f32_e32 v73, v64, v65
	v_add_f32_e32 v70, 1.0, v70
	v_rcp_f32_e32 v70, v70
	v_mul_f32_e32 v64, v69, v71
	v_mul_f32_e32 v68, v68, v64
	v_or_b32_e32 v69, 48, v144
	v_mul_f32_e32 v64, v67, v70
	v_fmamk_f32 v70, v169, 0x3a000000, v152
	v_rsq_f32_e32 v70, v70
	v_mul_f32_e32 v67, v66, v64
	v_cvt_pk_bf16_f32 v64, v80, v79
	v_cvt_pk_bf16_f32 v65, v76, v74
	v_cvt_pk_bf16_f32 v66, v72, v73
	v_mov_b32_e32 v72, v56
	v_mov_b32_e32 v73, v60
	v_pk_mul_f32 v[72:73], v[72:73], v[70:71] op_sel_hi:[1,0]
	v_mov_b32_e32 v60, v57
	v_mul_f32_e32 v56, 0xbfb8aa3b, v73
	v_exp_f32_e32 v71, v56
	v_cvt_pk_bf16_f32 v67, v68, v67
	v_mad_i64_i32 v[68:69], s[18:19], v69, s38, v[120:121]
	v_pk_mul_f32 v[56:57], v[60:61], v[70:71] op_sel_hi:[1,0]
	v_add_f32_e32 v61, 1.0, v71
	v_mul_f32_e32 v60, 0xbfb8aa3b, v57
	v_exp_f32_e32 v60, v60
	v_rcp_f32_e32 v61, v61
	v_lshl_add_u64 v[68:69], v[68:69], 0, v[104:105]
	global_store_dwordx4 v[68:69], v[64:67], off
	v_add_f32_e32 v60, 1.0, v60
	v_rcp_f32_e32 v60, v60
	v_mul_f32_e32 v61, v73, v61
	v_mul_f32_e32 v65, v72, v61
	v_mov_b32_e32 v61, v62
	v_mul_f32_e32 v57, v57, v60
	v_mov_b32_e32 v60, v58
	v_pk_mul_f32 v[60:61], v[60:61], v[70:71] op_sel_hi:[1,0]
	v_mov_b32_e32 v62, v59
	v_mul_f32_e32 v58, 0xbfb8aa3b, v61
	v_exp_f32_e32 v66, v58
	v_pk_mul_f32 v[58:59], v[62:63], v[70:71] op_sel_hi:[1,0]
	v_mul_f32_e32 v63, v56, v57
	v_mul_f32_e32 v62, 0xbfb8aa3b, v59
	v_exp_f32_e32 v62, v62
	v_add_f32_e32 v56, 1.0, v66
	v_rcp_f32_e32 v66, v56
	v_mov_b32_e32 v57, v52
	v_add_f32_e32 v56, 1.0, v62
	v_rcp_f32_e32 v62, v56
	v_mov_b32_e32 v56, v48
	v_pk_mul_f32 v[56:57], v[56:57], v[70:71] op_sel_hi:[1,0]
	v_mul_f32_e32 v52, v61, v66
	v_mul_f32_e32 v48, 0xbfb8aa3b, v57
	v_exp_f32_e32 v48, v48
	v_mul_f32_e32 v60, v60, v52
	v_mov_b32_e32 v52, v49
	v_mul_f32_e32 v59, v59, v62
	v_add_f32_e32 v48, 1.0, v48
	v_rcp_f32_e32 v61, v48
	v_pk_mul_f32 v[48:49], v[52:53], v[70:71] op_sel_hi:[1,0]
	v_mul_f32_e32 v58, v58, v59
	v_mul_f32_e32 v52, 0xbfb8aa3b, v49
	v_exp_f32_e32 v52, v52
	v_mul_f32_e32 v53, v57, v61
	v_mul_f32_e32 v56, v56, v53
	v_mov_b32_e32 v53, v54
	v_add_f32_e32 v52, 1.0, v52
	v_rcp_f32_e32 v57, v52
	v_mov_b32_e32 v52, v50
	v_pk_mul_f32 v[52:53], v[52:53], v[70:71] op_sel_hi:[1,0]
	v_mov_b32_e32 v54, v51
	v_mul_f32_e32 v50, 0xbfb8aa3b, v53
	v_exp_f32_e32 v59, v50
	v_pk_mul_f32 v[50:51], v[54:55], v[70:71] op_sel_hi:[1,0]
	v_mul_f32_e32 v49, v49, v57
	v_mul_f32_e32 v54, 0xbfb8aa3b, v51
	v_exp_f32_e32 v54, v54
	v_add_f32_e32 v55, 1.0, v59
	v_rcp_f32_e32 v55, v55
	v_mul_f32_e32 v57, v48, v49
	v_add_f32_e32 v54, 1.0, v54
	v_rcp_f32_e32 v54, v54
	v_mul_f32_e32 v48, v53, v55
	v_mul_f32_e32 v52, v52, v48
	v_add_u32_e32 v64, 0x80, v144
	v_mul_f32_e32 v48, v51, v54
	v_mul_f32_e32 v51, v50, v48
	v_cvt_pk_bf16_f32 v48, v65, v63
	v_cvt_pk_bf16_f32 v49, v60, v58
	v_cvt_pk_bf16_f32 v50, v56, v57
	v_cvt_pk_bf16_f32 v51, v52, v51
	v_fmamk_f32 v52, v124, 0x3a000000, v152
	v_rsq_f32_e32 v52, v52
	v_mov_b32_e32 v56, v40
	v_mov_b32_e32 v57, v44
	v_mov_b32_e32 v44, v41
	v_pk_mul_f32 v[56:57], v[56:57], v[52:53] op_sel_hi:[1,0]
	v_mad_i64_i32 v[54:55], s[18:19], v64, s38, v[120:121]
	v_mul_f32_e32 v40, 0xbfb8aa3b, v57
	v_exp_f32_e32 v53, v40
	s_nop 0
	v_pk_mul_f32 v[40:41], v[44:45], v[52:53] op_sel_hi:[1,0]
	v_add_f32_e32 v53, 1.0, v53
	v_rcp_f32_e32 v53, v53
	v_mul_f32_e32 v44, 0xbfb8aa3b, v41
	v_exp_f32_e32 v58, v44
	v_lshl_add_u64 v[44:45], v[54:55], 0, v[104:105]
	global_store_dwordx4 v[44:45], v[48:51], off
	v_mul_f32_e32 v44, v57, v53
	v_mov_b32_e32 v45, v46
	v_mul_f32_e32 v48, v56, v44
	v_mov_b32_e32 v44, v42
	v_pk_mul_f32 v[44:45], v[44:45], v[52:53] op_sel_hi:[1,0]
	v_add_f32_e32 v54, 1.0, v58
	v_mul_f32_e32 v42, 0xbfb8aa3b, v45
	v_mov_b32_e32 v46, v43
	v_rcp_f32_e32 v54, v54
	v_exp_f32_e32 v49, v42
	v_pk_mul_f32 v[42:43], v[46:47], v[52:53] op_sel_hi:[1,0]
	v_mul_f32_e32 v41, v41, v54
	v_mul_f32_e32 v46, 0xbfb8aa3b, v43
	v_exp_f32_e32 v46, v46
	v_mul_f32_e32 v47, v40, v41
	v_add_f32_e32 v40, 1.0, v49
	v_rcp_f32_e32 v49, v40
	v_add_f32_e32 v40, 1.0, v46
	v_rcp_f32_e32 v46, v40
	v_mov_b32_e32 v40, v32
	v_mov_b32_e32 v41, v36
	v_pk_mul_f32 v[40:41], v[40:41], v[52:53] op_sel_hi:[1,0]
	v_mul_f32_e32 v36, v45, v49
	v_mul_f32_e32 v32, 0xbfb8aa3b, v41
	v_exp_f32_e32 v32, v32
	v_mul_f32_e32 v44, v44, v36
	v_mov_b32_e32 v36, v33
	v_mul_f32_e32 v43, v43, v46
	v_add_f32_e32 v32, 1.0, v32
	v_rcp_f32_e32 v45, v32
	v_pk_mul_f32 v[32:33], v[36:37], v[52:53] op_sel_hi:[1,0]
	v_mul_f32_e32 v42, v42, v43
	v_mul_f32_e32 v36, 0xbfb8aa3b, v33
	v_exp_f32_e32 v36, v36
	v_mul_f32_e32 v37, v41, v45
	v_mul_f32_e32 v40, v40, v37
	v_mov_b32_e32 v37, v38
	v_add_f32_e32 v36, 1.0, v36
	v_rcp_f32_e32 v41, v36
	v_mov_b32_e32 v36, v34
	v_pk_mul_f32 v[36:37], v[36:37], v[52:53] op_sel_hi:[1,0]
	v_mov_b32_e32 v38, v35
	v_mul_f32_e32 v34, 0xbfb8aa3b, v37
	v_exp_f32_e32 v43, v34
	v_pk_mul_f32 v[34:35], v[38:39], v[52:53] op_sel_hi:[1,0]
	v_mul_f32_e32 v33, v33, v41
; __device__ __forceinline__ unsigned cvt_pk_bf16(float lo, float hi) { unsigned r; asm volatile("v_cvt_pk_bf16_f32 %0, %1, %2" : "=v"(r) : "v"(lo), "v"(hi)); return r; }
; __device__ __forceinline__ float sigm(float x) { return __builtin_amdgcn_rcpf(1.f + __builtin_amdgcn_exp2f(-LOG2E * x)); }
; #define PG8_WAIT_V(n) asm volatile("s_waitcnt vmcnt(" #n ")" ::: "memory")
; #define PG8_BAR __builtin_amdgcn_s_barrier()
;     __device__ __forceinline__ void operator()(const f32x4 (&acc)[2][2][4][2], const Unit& u, int wr, int wc, int fr, int fq) const {
;     ...
;         for (int ai = 0; ai < 2; ++ai)
; #pragma unroll
;             for (int m = 0; m < 4; ++m) {
;                 const int r = row0 + ai * HALF + m * 16; const float rs = __builtin_amdgcn_rsqf(sq[ai * 4 + m] * (1.f / 2048.f) + EPS);
;                 float v[8];
; #pragma unroll
;                 for (int n = 0; n < 2; ++n)
; #pragma unroll
;                     for (int j = 0; j < 4; ++j) { const float g = acc[ai][0][m][n][j] * rs, up = acc[ai][1][m][n][j] * rs; v[n * 4 + j] = g * sigm(g) * up; }
;                 u32x4 w; w.x = cvt_pk_bf16(v[0], v[1]); w.y = cvt_pk_bf16(v[2], v[3]); w.z = cvt_pk_bf16(v[4], v[5]); w.w = cvt_pk_bf16(v[6], v[7]);
;                 *(u32x4*)(O + (size_t)r * FF + col0) = w;
;             }
; template <class Epi, class Sched>
; __device__ __forceinline__ void gemm_phase(LAS unsigned char* lds, const Gemm g, const Sched& S, const Epi& E) {
;     ...
;     PG8_WAIT_V(0);
;     if (wr == 0) PG8_BAR;
;     PG8_BAR;
	v_mul_f32_e32 v38, 0xbfb8aa3b, v35
	v_exp_f32_e32 v38, v38
	v_add_f32_e32 v39, 1.0, v43
	v_rcp_f32_e32 v39, v39
	v_mul_f32_e32 v41, v32, v33
	v_add_f32_e32 v38, 1.0, v38
	v_rcp_f32_e32 v38, v38
	v_mul_f32_e32 v32, v37, v39
	v_mul_f32_e32 v36, v36, v32
	v_add_u32_e32 v37, 0x90, v144
	v_mul_f32_e32 v32, v35, v38
	v_mul_f32_e32 v35, v34, v32
	v_cvt_pk_bf16_f32 v32, v48, v47
	v_cvt_pk_bf16_f32 v33, v44, v42
	v_cvt_pk_bf16_f32 v34, v40, v41
	v_cvt_pk_bf16_f32 v35, v36, v35
	v_fmamk_f32 v36, v123, 0x3a000000, v152
	v_rsq_f32_e32 v36, v36
	v_mov_b32_e32 v40, v24
	v_mov_b32_e32 v41, v28
	v_mad_i64_i32 v[38:39], s[18:19], v37, s38, v[120:121]
	v_pk_mul_f32 v[40:41], v[40:41], v[36:37] op_sel_hi:[1,0]
	v_mov_b32_e32 v28, v25
	v_mul_f32_e32 v24, 0xbfb8aa3b, v41
	v_exp_f32_e32 v37, v24
	s_nop 0
	v_pk_mul_f32 v[24:25], v[28:29], v[36:37] op_sel_hi:[1,0]
	v_add_f32_e32 v37, 1.0, v37
	v_rcp_f32_e32 v37, v37
	v_mul_f32_e32 v28, 0xbfb8aa3b, v25
	v_exp_f32_e32 v42, v28
	v_lshl_add_u64 v[28:29], v[38:39], 0, v[104:105]
	global_store_dwordx4 v[28:29], v[32:35], off
	v_mul_f32_e32 v28, v41, v37
	v_mov_b32_e32 v29, v30
	v_mul_f32_e32 v32, v40, v28
	v_mov_b32_e32 v28, v26
	v_pk_mul_f32 v[28:29], v[28:29], v[36:37] op_sel_hi:[1,0]
	v_add_f32_e32 v38, 1.0, v42
	v_mul_f32_e32 v26, 0xbfb8aa3b, v29
	v_mov_b32_e32 v30, v27
	v_rcp_f32_e32 v38, v38
	v_exp_f32_e32 v33, v26
	v_pk_mul_f32 v[26:27], v[30:31], v[36:37] op_sel_hi:[1,0]
	v_mul_f32_e32 v25, v25, v38
	v_mul_f32_e32 v30, 0xbfb8aa3b, v27
	v_exp_f32_e32 v30, v30
	v_mul_f32_e32 v31, v24, v25
	v_add_f32_e32 v24, 1.0, v33
	v_rcp_f32_e32 v33, v24
	v_add_f32_e32 v24, 1.0, v30
	v_rcp_f32_e32 v30, v24
	v_mov_b32_e32 v24, v16
	v_mov_b32_e32 v25, v20
	v_pk_mul_f32 v[24:25], v[24:25], v[36:37] op_sel_hi:[1,0]
	v_mul_f32_e32 v20, v29, v33
	v_mul_f32_e32 v16, 0xbfb8aa3b, v25
	v_exp_f32_e32 v16, v16
	v_mul_f32_e32 v28, v28, v20
	v_mov_b32_e32 v20, v17
	v_mul_f32_e32 v27, v27, v30
	v_add_f32_e32 v16, 1.0, v16
	v_rcp_f32_e32 v29, v16
	v_pk_mul_f32 v[16:17], v[20:21], v[36:37] op_sel_hi:[1,0]
	v_mul_f32_e32 v26, v26, v27
	v_mul_f32_e32 v20, 0xbfb8aa3b, v17
	v_exp_f32_e32 v20, v20
	v_mul_f32_e32 v21, v25, v29
	v_mul_f32_e32 v24, v24, v21
	v_mov_b32_e32 v21, v22
	v_add_f32_e32 v20, 1.0, v20
	v_rcp_f32_e32 v25, v20
	v_mov_b32_e32 v20, v18
	v_pk_mul_f32 v[20:21], v[20:21], v[36:37] op_sel_hi:[1,0]
	v_mov_b32_e32 v22, v19
	v_mul_f32_e32 v18, 0xbfb8aa3b, v21
	v_exp_f32_e32 v27, v18
	v_pk_mul_f32 v[18:19], v[22:23], v[36:37] op_sel_hi:[1,0]
	v_mul_f32_e32 v17, v17, v25
	v_mul_f32_e32 v22, 0xbfb8aa3b, v19
	v_exp_f32_e32 v22, v22
	v_add_f32_e32 v23, 1.0, v27
	v_rcp_f32_e32 v23, v23
	v_mul_f32_e32 v25, v16, v17
	v_add_f32_e32 v22, 1.0, v22
	v_rcp_f32_e32 v22, v22
	v_mul_f32_e32 v16, v21, v23
	v_mul_f32_e32 v20, v20, v16
	v_add_u32_e32 v21, 0xa0, v144
	v_mul_f32_e32 v16, v19, v22
	v_mul_f32_e32 v19, v18, v16
	v_cvt_pk_bf16_f32 v16, v32, v31
	v_cvt_pk_bf16_f32 v17, v28, v26
	v_cvt_pk_bf16_f32 v18, v24, v25
	v_cvt_pk_bf16_f32 v19, v20, v19
	v_fmamk_f32 v20, v190, 0x3a000000, v152
	v_rsq_f32_e32 v20, v20
	v_mov_b32_e32 v24, v8
	v_mov_b32_e32 v25, v12
	v_mad_i64_i32 v[22:23], s[18:19], v21, s38, v[120:121]
	v_pk_mul_f32 v[24:25], v[24:25], v[20:21] op_sel_hi:[1,0]
	v_mov_b32_e32 v12, v9
	v_mul_f32_e32 v8, 0xbfb8aa3b, v25
	v_exp_f32_e32 v21, v8
	s_nop 0
	v_pk_mul_f32 v[8:9], v[12:13], v[20:21] op_sel_hi:[1,0]
	v_add_f32_e32 v21, 1.0, v21
	v_rcp_f32_e32 v21, v21
	v_mul_f32_e32 v12, 0xbfb8aa3b, v9
	v_exp_f32_e32 v26, v12
	v_lshl_add_u64 v[12:13], v[22:23], 0, v[104:105]
	global_store_dwordx4 v[12:13], v[16:19], off
	v_mul_f32_e32 v12, v25, v21
	v_mov_b32_e32 v13, v14
	v_mul_f32_e32 v16, v24, v12
	v_mov_b32_e32 v12, v10
	v_pk_mul_f32 v[12:13], v[12:13], v[20:21] op_sel_hi:[1,0]
	v_add_f32_e32 v22, 1.0, v26
	v_mul_f32_e32 v10, 0xbfb8aa3b, v13
	v_mov_b32_e32 v14, v11
	v_rcp_f32_e32 v22, v22
	v_exp_f32_e32 v17, v10
	v_pk_mul_f32 v[10:11], v[14:15], v[20:21] op_sel_hi:[1,0]
	v_mul_f32_e32 v9, v9, v22
	v_mul_f32_e32 v14, 0xbfb8aa3b, v11
	v_exp_f32_e32 v14, v14
	v_mul_f32_e32 v15, v8, v9
	v_add_f32_e32 v8, 1.0, v17
	v_rcp_f32_e32 v17, v8
	v_add_f32_e32 v8, 1.0, v14
	v_rcp_f32_e32 v14, v8
	v_mov_b32_e32 v8, v0
	v_mov_b32_e32 v9, v4
	v_pk_mul_f32 v[8:9], v[8:9], v[20:21] op_sel_hi:[1,0]
	v_mul_f32_e32 v4, v13, v17
	v_mul_f32_e32 v0, 0xbfb8aa3b, v9
	v_exp_f32_e32 v0, v0
	v_mul_f32_e32 v12, v12, v4
	v_mov_b32_e32 v4, v1
	v_mul_f32_e32 v11, v11, v14
	v_add_f32_e32 v0, 1.0, v0
	v_rcp_f32_e32 v13, v0
	v_pk_mul_f32 v[0:1], v[4:5], v[20:21] op_sel_hi:[1,0]
	v_mul_f32_e32 v10, v10, v11
	v_mul_f32_e32 v4, 0xbfb8aa3b, v1
	v_exp_f32_e32 v4, v4
	v_mul_f32_e32 v5, v9, v13
	v_mul_f32_e32 v8, v8, v5
	v_mov_b32_e32 v5, v6
	v_add_f32_e32 v4, 1.0, v4
	v_rcp_f32_e32 v9, v4
	v_mov_b32_e32 v4, v2
	v_pk_mul_f32 v[4:5], v[4:5], v[20:21] op_sel_hi:[1,0]
	v_mov_b32_e32 v6, v3
	v_mul_f32_e32 v2, 0xbfb8aa3b, v5
	v_exp_f32_e32 v11, v2
	v_pk_mul_f32 v[2:3], v[6:7], v[20:21] op_sel_hi:[1,0]
	v_mul_f32_e32 v1, v1, v9
	v_mul_f32_e32 v6, 0xbfb8aa3b, v3
	v_exp_f32_e32 v6, v6
	v_add_f32_e32 v7, 1.0, v11
	v_rcp_f32_e32 v7, v7
	v_mul_f32_e32 v9, v0, v1
	v_add_f32_e32 v6, 1.0, v6
	v_rcp_f32_e32 v6, v6
	v_mul_f32_e32 v0, v5, v7
	v_mul_f32_e32 v4, v4, v0
	v_add_u32_e32 v5, 0xb0, v144
	v_mul_f32_e32 v0, v3, v6
	v_mul_f32_e32 v3, v2, v0
	v_cvt_pk_bf16_f32 v0, v16, v15
	v_cvt_pk_bf16_f32 v1, v12, v10
	v_cvt_pk_bf16_f32 v2, v8, v9
	v_cvt_pk_bf16_f32 v3, v4, v3
	v_mad_i64_i32 v[4:5], s[18:19], v5, s38, v[120:121]
	v_lshl_add_u64 v[4:5], v[4:5], 0, v[104:105]
	s_mov_b64 s[18:19], s[12:13]
	global_store_dwordx4 v[4:5], v[0:3], off
	s_cbranch_vccz .LBB0_862
	s_waitcnt vmcnt(0)
	s_cmpk_gt_u32 s24, 0xff
	s_cbranch_scc1 .LBB0_869
	s_barrier

; #define PG8_STAGE(bufoff, gbase, voff) do { _Pragma("unroll") for (int _i = 0; _i < 2; ++_i) \
;         __builtin_amdgcn_global_load_lds((const unsigned*)((const char*)(gbase) + (voff)[_i]), (LAS unsigned*)(lds + (bufoff) + ldsw + _i * 8192), 16, 0, 0); } while (0)
; #define PG8_LDA(dst, b, h) do { _Pragma("unroll") for (int m = 0; m < 4; ++m) _Pragma("unroll") for (int k = 0; k < 2; ++k) dst[m][k] = *(const LAS bf16x8*)(lds + PG8_SA(b, h) + aoff + m * 2048 + k * 1024); } while (0)
; #define PG8_LDB(dst, b, h) do { _Pragma("unroll") for (int n = 0; n < 2; ++n) _Pragma("unroll") for (int k = 0; k < 2; ++k) dst[n][k] = *(const LAS bf16x8*)(lds + PG8_SB(b, h) + boff + n * 2048 + k * 1024); } while (0)
; #define PG8_MMA(ai, bj, At, Bt) do { __builtin_amdgcn_s_setprio(1); _Pragma("unroll") for (int m = 0; m < 4; ++m) _Pragma("unroll") for (int n = 0; n < 2; ++n) _Pragma("unroll") for (int k = 0; k < 2; ++k) \
;         acc[ai][bj][m][n] = MmaOp<Epi::I8>::run(Bt[n][k], At[m][k], acc[ai][bj][m][n]); __builtin_amdgcn_s_setprio(0); } while (0)
; #define PG8_WAIT_L(n) asm volatile("s_waitcnt lgkmcnt(" #n ")" ::: "memory")
; #define PG8_BAR __builtin_amdgcn_s_barrier()
; template <class Epi, class Sched>
; __device__ __forceinline__ void gemm_phase(LAS unsigned char* lds, const Gemm g, const Sched& S, const Epi& E) {
;     ...
;         for (int t = 0; t < nt; t += 2) {
;             const bool last = (t == nt - 2);
;             const char* a1 = cA + (size_t)(t + 1) * kstep;
;             const char* a2 = last ? nA : cA + (size_t)(t + 2) * kstep; const char* b2 = last ? nB : cB + (size_t)(t + 2) * kstep;
;             const char* a3 = a2 + kstep; const char* b3 = b2 + kstep;
;             PG8_LDB(B0, 0, 0); PG8_SCHED; PG8_LDA(At, 0, 0); PG8_STAGE(PG8_SA(1, 1), a1 + hstepA, voffA);
;             PG8_WAIT_L(8); PG8_BAR; PG8_WAIT_L(0); PG8_MMA(0, 0, At, B0); PG8_BAR; PG8_SCHED;
;             PG8_LDB(B1, 0, 1); PG8_STAGE(PG8_SB(0, 0), b2, voffB);
;             PG8_BAR; PG8_WAIT_L(0); PG8_MMA(0, 1, At, B1); PG8_BAR;
;     ...
; #pragma unroll
;         for (int a = 0; a < 2; ++a)
; #pragma unroll
;             for (int b = 0; b < 2; ++b)
; #pragma unroll
;                 for (int m = 0; m < 4; ++m)
; #pragma unroll
;                     for (int n = 0; n < 2; ++n) acc[a][b][m][n] = (acc_t){0, 0, 0, 0};
;         cur = nxt; cA = nA; cB = nB; ++ui;
.LBB0_935:
	s_add_u32 s12, s12, 0x158080
	s_addc_u32 s13, s13, 0
	s_add_u32 s43, s14, 0x100
	v_mov_b32_e32 v0, 0
	s_addc_u32 s44, s15, 0
	s_mov_b32 s45, -2
	v_mov_b32_e32 v1, v0
	v_mov_b32_e32 v2, v0
	v_mov_b32_e32 v3, v0
	v_mov_b32_e32 v4, v0
	v_mov_b32_e32 v5, v0
	v_mov_b32_e32 v6, v0
	v_mov_b32_e32 v7, v0
	v_mov_b32_e32 v8, v0
	v_mov_b32_e32 v9, v0
	v_mov_b32_e32 v10, v0
	v_mov_b32_e32 v11, v0
	v_mov_b32_e32 v12, v0
	v_mov_b32_e32 v13, v0
	v_mov_b32_e32 v14, v0
	v_mov_b32_e32 v15, v0
	v_mov_b32_e32 v32, v0
	v_mov_b32_e32 v33, v0
	v_mov_b32_e32 v34, v0
	v_mov_b32_e32 v35, v0
	v_mov_b32_e32 v36, v0
	v_mov_b32_e32 v37, v0
	v_mov_b32_e32 v38, v0
	v_mov_b32_e32 v39, v0
	v_mov_b32_e32 v40, v0
	v_mov_b32_e32 v41, v0
	v_mov_b32_e32 v42, v0
	v_mov_b32_e32 v43, v0
	v_mov_b32_e32 v44, v0
	v_mov_b32_e32 v45, v0
	v_mov_b32_e32 v46, v0
	v_mov_b32_e32 v47, v0
	v_mov_b32_e32 v16, v0
	v_mov_b32_e32 v17, v0
	v_mov_b32_e32 v18, v0
	v_mov_b32_e32 v19, v0
	v_mov_b32_e32 v20, v0
	v_mov_b32_e32 v21, v0
	v_mov_b32_e32 v22, v0
	v_mov_b32_e32 v23, v0
	v_mov_b32_e32 v24, v0
	v_mov_b32_e32 v25, v0
	v_mov_b32_e32 v26, v0
	v_mov_b32_e32 v27, v0
	v_mov_b32_e32 v28, v0
	v_mov_b32_e32 v29, v0
	v_mov_b32_e32 v30, v0
	v_mov_b32_e32 v31, v0
	v_mov_b32_e32 v48, v0
	v_mov_b32_e32 v49, v0
	v_mov_b32_e32 v50, v0
	v_mov_b32_e32 v51, v0
	v_mov_b32_e32 v52, v0
	v_mov_b32_e32 v53, v0
	v_mov_b32_e32 v54, v0
	v_mov_b32_e32 v55, v0
	v_mov_b32_e32 v56, v0
	v_mov_b32_e32 v57, v0
	v_mov_b32_e32 v58, v0
	v_mov_b32_e32 v59, v0
	v_mov_b32_e32 v60, v0
	v_mov_b32_e32 v61, v0
	v_mov_b32_e32 v62, v0
	v_mov_b32_e32 v63, v0
	v_mov_b32_e32 v64, v0
	v_mov_b32_e32 v65, v0
	v_mov_b32_e32 v66, v0
	v_mov_b32_e32 v67, v0
	v_mov_b32_e32 v68, v0
	v_mov_b32_e32 v69, v0
	v_mov_b32_e32 v70, v0
	v_mov_b32_e32 v71, v0
	v_mov_b32_e32 v72, v0
	v_mov_b32_e32 v73, v0
	v_mov_b32_e32 v74, v0
	v_mov_b32_e32 v75, v0
	v_mov_b32_e32 v76, v0
	v_mov_b32_e32 v77, v0
	v_mov_b32_e32 v78, v0
	v_mov_b32_e32 v79, v0
	v_mov_b32_e32 v96, v0
	v_mov_b32_e32 v97, v0
	v_mov_b32_e32 v98, v0
	v_mov_b32_e32 v99, v0
	v_mov_b32_e32 v100, v0
	v_mov_b32_e32 v101, v0
	v_mov_b32_e32 v102, v0
	v_mov_b32_e32 v103, v0
	v_mov_b32_e32 v104, v0
	v_mov_b32_e32 v105, v0
	v_mov_b32_e32 v106, v0
	v_mov_b32_e32 v107, v0
	v_mov_b32_e32 v108, v0
	v_mov_b32_e32 v109, v0
	v_mov_b32_e32 v110, v0
	v_mov_b32_e32 v111, v0
	v_mov_b32_e32 v80, v0
	v_mov_b32_e32 v81, v0
	v_mov_b32_e32 v82, v0
	v_mov_b32_e32 v83, v0
	v_mov_b32_e32 v84, v0
	v_mov_b32_e32 v85, v0
	v_mov_b32_e32 v86, v0
	v_mov_b32_e32 v87, v0
	v_mov_b32_e32 v88, v0
	v_mov_b32_e32 v89, v0
	v_mov_b32_e32 v90, v0
	v_mov_b32_e32 v91, v0
	v_mov_b32_e32 v92, v0
	v_mov_b32_e32 v93, v0
	v_mov_b32_e32 v94, v0
	v_mov_b32_e32 v95, v0
	v_mov_b32_e32 v112, v0
	v_mov_b32_e32 v113, v0
	v_mov_b32_e32 v114, v0
	v_mov_b32_e32 v115, v0
	v_mov_b32_e32 v116, v0
	v_mov_b32_e32 v117, v0
	v_mov_b32_e32 v118, v0
	v_mov_b32_e32 v119, v0
	v_mov_b32_e32 v120, v0
	v_mov_b32_e32 v121, v0
	v_mov_b32_e32 v122, v0
	v_mov_b32_e32 v123, v0
	v_mov_b32_e32 v124, v0
	v_mov_b32_e32 v125, v0
	v_mov_b32_e32 v126, v0
	v_mov_b32_e32 v127, v0
.LBB0_936:
	ds_read_b128 v[140:143], v149
	ds_read_b128 v[152:155], v149 offset:1024
	ds_read_b128 v[156:159], v149 offset:2048
	ds_read_b128 v[160:163], v149 offset:3072
	s_add_u32 s14, s12, 0xffea8080
	s_addc_u32 s15, s13, -1
	s_cmpk_eq_i32 s45, 0x52
	s_cselect_b32 s17, s5, s15
	s_cselect_b32 s16, s4, s14
	s_cselect_b32 s15, s7, s44
	s_cselect_b32 s14, s6, s43
	v_lshl_add_u64 v[144:145], s[12:13], 0, v[132:133]
	s_add_i32 m0, s22, 0xc000
	ds_read_b128 v[164:167], v150
	ds_read_b128 v[168:171], v150 offset:1024
	ds_read_b128 v[172:175], v150 offset:2048
	ds_read_b128 v[178:181], v150 offset:3072
	ds_read_b128 v[182:185], v150 offset:4096
	ds_read_b128 v[186:189], v150 offset:5120
	ds_read_b128 v[190:193], v150 offset:6144
	ds_read_b128 v[194:197], v150 offset:7168
	global_load_lds_dwordx4 v[144:145], off
	v_lshl_add_u64 v[144:145], s[12:13], 0, v[134:135]
	s_add_i32 m0, s22, 0xe000
	s_nop 0
	global_load_lds_dwordx4 v[144:145], off
	s_waitcnt lgkmcnt(8)
	s_barrier
	s_waitcnt lgkmcnt(0)
	s_setprio 1
	s_waitcnt lgkmcnt(0)
	v_mfma_f32_16x16x32_bf16 v[124:127], v[140:143], v[164:167], v[124:127]
	v_mfma_f32_16x16x32_bf16 v[120:123], v[156:159], v[164:167], v[120:123]
	v_mfma_f32_16x16x32_bf16 v[116:119], v[140:143], v[172:175], v[116:119]
	v_mfma_f32_16x16x32_bf16 v[112:115], v[156:159], v[172:175], v[112:115]
	v_mfma_f32_16x16x32_bf16 v[92:95], v[140:143], v[182:185], v[92:95]
	v_mfma_f32_16x16x32_bf16 v[88:91], v[156:159], v[182:185], v[88:91]
	v_mfma_f32_16x16x32_bf16 v[84:87], v[140:143], v[190:193], v[84:87]
	v_mfma_f32_16x16x32_bf16 v[80:83], v[156:159], v[190:193], v[80:83]
	v_mfma_f32_16x16x32_bf16 v[124:127], v[152:155], v[168:171], v[124:127]
	v_mfma_f32_16x16x32_bf16 v[120:123], v[160:163], v[168:171], v[120:123]
	v_mfma_f32_16x16x32_bf16 v[116:119], v[152:155], v[178:181], v[116:119]
	v_mfma_f32_16x16x32_bf16 v[112:115], v[160:163], v[178:181], v[112:115]
	v_mfma_f32_16x16x32_bf16 v[92:95], v[152:155], v[186:189], v[92:95]
	v_mfma_f32_16x16x32_bf16 v[88:91], v[160:163], v[186:189], v[88:91]
	v_mfma_f32_16x16x32_bf16 v[84:87], v[152:155], v[194:197], v[84:87]
	v_mfma_f32_16x16x32_bf16 v[80:83], v[160:163], v[194:197], v[80:83]
	s_setprio 0
	s_barrier
	s_add_i32 s46, s30, s19
	v_lshl_add_u64 v[144:145], s[14:15], 0, v[130:131]
	s_mov_b32 m0, s46
	ds_read_b128 v[198:201], v151
	ds_read_b128 v[202:205], v151 offset:1024
	ds_read_b128 v[206:209], v151 offset:2048
	ds_read_b128 v[210:213], v151 offset:3072
	global_load_lds_dwordx4 v[144:145], off
	v_lshl_add_u64 v[214:215], s[14:15], 0, v[128:129]
	s_add_i32 m0, s46, 0x2000
	s_nop 0
	global_load_lds_dwordx4 v[214:215], off
	s_barrier
; #define PG8_STAGE(bufoff, gbase, voff) do { _Pragma("unroll") for (int _i = 0; _i < 2; ++_i) \
;         __builtin_amdgcn_global_load_lds((const unsigned*)((const char*)(gbase) + (voff)[_i]), (LAS unsigned*)(lds + (bufoff) + ldsw + _i * 8192), 16, 0, 0); } while (0)
; #define PG8_LDA(dst, b, h) do { _Pragma("unroll") for (int m = 0; m < 4; ++m) _Pragma("unroll") for (int k = 0; k < 2; ++k) dst[m][k] = *(const LAS bf16x8*)(lds + PG8_SA(b, h) + aoff + m * 2048 + k * 1024); } while (0)
; #define PG8_LDB(dst, b, h) do { _Pragma("unroll") for (int n = 0; n < 2; ++n) _Pragma("unroll") for (int k = 0; k < 2; ++k) dst[n][k] = *(const LAS bf16x8*)(lds + PG8_SB(b, h) + boff + n * 2048 + k * 1024); } while (0)
; #define PG8_MMA(ai, bj, At, Bt) do { __builtin_amdgcn_s_setprio(1); _Pragma("unroll") for (int m = 0; m < 4; ++m) _Pragma("unroll") for (int n = 0; n < 2; ++n) _Pragma("unroll") for (int k = 0; k < 2; ++k) \
;         acc[ai][bj][m][n] = MmaOp<Epi::I8>::run(Bt[n][k], At[m][k], acc[ai][bj][m][n]); __builtin_amdgcn_s_setprio(0); } while (0)
; #define PG8_WAIT_V(n) asm volatile("s_waitcnt vmcnt(" #n ")" ::: "memory")
; #define PG8_WAIT_L(n) asm volatile("s_waitcnt lgkmcnt(" #n ")" ::: "memory")
; #define PG8_BAR __builtin_amdgcn_s_barrier()
; #define PG8_SCHED __builtin_amdgcn_sched_barrier(0)
; template <class Epi, class Sched>
; __device__ __forceinline__ void gemm_phase(LAS unsigned char* lds, const Gemm g, const Sched& S, const Epi& E) {
;     ...
;             PG8_BAR; PG8_WAIT_L(0); PG8_MMA(0, 1, At, B1); PG8_BAR;
;             PG8_LDA(At, 0, 1); PG8_STAGE(PG8_SA(0, 0), a2, voffA);
;             PG8_BAR; PG8_WAIT_L(0); PG8_MMA(1, 0, At, B0); PG8_BAR; PG8_SCHED;
;             PG8_STAGE(PG8_SB(0, 1), b2 + hstepB, voffB);
;             PG8_WAIT_V(6); PG8_BAR; PG8_MMA(1, 1, At, B1); PG8_BAR;
;             PG8_LDB(B0, 1, 0); PG8_SCHED; PG8_LDA(At, 1, 0); PG8_STAGE(PG8_SA(0, 1), a2 + hstepA, voffA);
;             PG8_WAIT_L(8); PG8_BAR; PG8_WAIT_L(0); PG8_MMA(0, 0, At, B0); PG8_BAR; PG8_SCHED;
;             PG8_LDB(B1, 1, 1); PG8_STAGE(PG8_SB(1, 0), b3, voffB);
;             PG8_BAR; PG8_WAIT_L(0); PG8_MMA(0, 1, At, B1); PG8_BAR;
	s_waitcnt lgkmcnt(0)
	s_setprio 1
	s_waitcnt lgkmcnt(0)
	v_mfma_f32_16x16x32_bf16 v[108:111], v[198:201], v[164:167], v[108:111]
	v_mfma_f32_16x16x32_bf16 v[104:107], v[206:209], v[164:167], v[104:107]
	v_mfma_f32_16x16x32_bf16 v[100:103], v[198:201], v[172:175], v[100:103]
	v_mfma_f32_16x16x32_bf16 v[96:99], v[206:209], v[172:175], v[96:99]
	v_mfma_f32_16x16x32_bf16 v[76:79], v[198:201], v[182:185], v[76:79]
	v_mfma_f32_16x16x32_bf16 v[72:75], v[206:209], v[182:185], v[72:75]
	v_mfma_f32_16x16x32_bf16 v[68:71], v[198:201], v[190:193], v[68:71]
	v_mfma_f32_16x16x32_bf16 v[64:67], v[206:209], v[190:193], v[64:67]
	v_mfma_f32_16x16x32_bf16 v[108:111], v[202:205], v[168:171], v[108:111]
	v_mfma_f32_16x16x32_bf16 v[104:107], v[210:213], v[168:171], v[104:107]
	v_mfma_f32_16x16x32_bf16 v[100:103], v[202:205], v[178:181], v[100:103]
	v_mfma_f32_16x16x32_bf16 v[96:99], v[210:213], v[178:181], v[96:99]
	v_mfma_f32_16x16x32_bf16 v[76:79], v[202:205], v[186:189], v[76:79]
	v_mfma_f32_16x16x32_bf16 v[72:75], v[210:213], v[186:189], v[72:75]
	v_mfma_f32_16x16x32_bf16 v[68:71], v[202:205], v[194:197], v[68:71]
	v_mfma_f32_16x16x32_bf16 v[64:67], v[210:213], v[194:197], v[64:67]
	s_setprio 0
	s_mov_b32 m0, s22
	v_lshl_add_u64 v[216:217], s[16:17], 0, v[130:131]
	s_barrier
	ds_read_b128 v[164:167], v150 offset:16384
	ds_read_b128 v[168:171], v150 offset:17408
	ds_read_b128 v[172:175], v150 offset:18432
	ds_read_b128 v[178:181], v150 offset:19456
	ds_read_b128 v[182:185], v150 offset:20480
	ds_read_b128 v[186:189], v150 offset:21504
	ds_read_b128 v[190:193], v150 offset:22528
	ds_read_b128 v[194:197], v150 offset:23552
	global_load_lds_dwordx4 v[216:217], off
	v_lshl_add_u64 v[218:219], s[16:17], 0, v[128:129]
	s_mov_b32 m0, s23
	s_nop 0
	global_load_lds_dwordx4 v[218:219], off
	s_barrier
	s_waitcnt lgkmcnt(0)
	s_setprio 1
	s_waitcnt lgkmcnt(0)
	v_mfma_f32_16x16x32_bf16 v[60:63], v[140:143], v[164:167], v[60:63]
	v_mfma_f32_16x16x32_bf16 v[56:59], v[156:159], v[164:167], v[56:59]
	v_mfma_f32_16x16x32_bf16 v[52:55], v[140:143], v[172:175], v[52:55]
	v_mfma_f32_16x16x32_bf16 v[48:51], v[156:159], v[172:175], v[48:51]
	v_mfma_f32_16x16x32_bf16 v[28:31], v[140:143], v[182:185], v[28:31]
	v_mfma_f32_16x16x32_bf16 v[24:27], v[156:159], v[182:185], v[24:27]
	v_mfma_f32_16x16x32_bf16 v[20:23], v[140:143], v[190:193], v[20:23]
	v_mfma_f32_16x16x32_bf16 v[16:19], v[156:159], v[190:193], v[16:19]
	v_mfma_f32_16x16x32_bf16 v[60:63], v[152:155], v[168:171], v[60:63]
	v_mfma_f32_16x16x32_bf16 v[56:59], v[160:163], v[168:171], v[56:59]
	v_mfma_f32_16x16x32_bf16 v[52:55], v[152:155], v[178:181], v[52:55]
	v_mfma_f32_16x16x32_bf16 v[48:51], v[160:163], v[178:181], v[48:51]
	v_mfma_f32_16x16x32_bf16 v[28:31], v[152:155], v[186:189], v[28:31]
	v_mfma_f32_16x16x32_bf16 v[24:27], v[160:163], v[186:189], v[24:27]
	v_mfma_f32_16x16x32_bf16 v[20:23], v[152:155], v[194:197], v[20:23]
	v_mfma_f32_16x16x32_bf16 v[16:19], v[160:163], v[194:197], v[16:19]
	s_setprio 0
	s_barrier
	s_add_u32 s46, s14, 0x158000
	s_addc_u32 s47, s15, 0
	s_add_i32 s48, s31, s19
	v_lshl_add_u64 v[140:141], s[46:47], 0, v[130:131]
	s_mov_b32 m0, s48
	s_nop 0
	global_load_lds_dwordx4 v[140:141], off
	v_lshl_add_u64 v[140:141], s[46:47], 0, v[128:129]
	s_add_i32 m0, s48, 0x2000
	s_nop 0
	global_load_lds_dwordx4 v[140:141], off
	s_waitcnt vmcnt(6)
	s_barrier
	s_setprio 1
	v_mfma_f32_16x16x32_bf16 v[44:47], v[198:201], v[164:167], v[44:47]
	v_mfma_f32_16x16x32_bf16 v[40:43], v[206:209], v[164:167], v[40:43]
	v_mfma_f32_16x16x32_bf16 v[36:39], v[198:201], v[172:175], v[36:39]
	v_mfma_f32_16x16x32_bf16 v[32:35], v[206:209], v[172:175], v[32:35]
	v_mfma_f32_16x16x32_bf16 v[12:15], v[198:201], v[182:185], v[12:15]
	v_mfma_f32_16x16x32_bf16 v[8:11], v[206:209], v[182:185], v[8:11]
	v_mfma_f32_16x16x32_bf16 v[4:7], v[198:201], v[190:193], v[4:7]
	v_mfma_f32_16x16x32_bf16 v[0:3], v[206:209], v[190:193], v[0:3]
	v_mfma_f32_16x16x32_bf16 v[44:47], v[202:205], v[168:171], v[44:47]
	v_mfma_f32_16x16x32_bf16 v[40:43], v[210:213], v[168:171], v[40:43]
	v_mfma_f32_16x16x32_bf16 v[36:39], v[202:205], v[178:181], v[36:39]
	v_mfma_f32_16x16x32_bf16 v[32:35], v[210:213], v[178:181], v[32:35]
	v_mfma_f32_16x16x32_bf16 v[12:15], v[202:205], v[186:189], v[12:15]
	v_mfma_f32_16x16x32_bf16 v[8:11], v[210:213], v[186:189], v[8:11]
	v_mfma_f32_16x16x32_bf16 v[4:7], v[202:205], v[194:197], v[4:7]
	v_mfma_f32_16x16x32_bf16 v[0:3], v[210:213], v[194:197], v[0:3]
	s_setprio 0
	s_add_i32 s46, 0, 0x18000
	v_add_u32_e32 v160, s46, v147
	s_barrier
	ds_read_b128 v[140:143], v160
	ds_read_b128 v[152:155], v160 offset:1024
	ds_read_b128 v[156:159], v160 offset:2048
	ds_read_b128 v[160:163], v160 offset:3072
	s_add_u32 s16, s16, 0x158000
	s_addc_u32 s17, s17, 0
	s_mov_b32 m0, s24
	v_lshl_add_u64 v[198:199], s[16:17], 0, v[130:131]
	ds_read_b128 v[164:167], v150 offset:32768
	ds_read_b128 v[168:171], v150 offset:33792
	ds_read_b128 v[172:175], v150 offset:34816
	ds_read_b128 v[178:181], v150 offset:35840
	ds_read_b128 v[182:185], v150 offset:36864
	ds_read_b128 v[186:189], v150 offset:37888
	ds_read_b128 v[190:193], v150 offset:38912
	ds_read_b128 v[194:197], v150 offset:39936
	global_load_lds_dwordx4 v[198:199], off
	v_lshl_add_u64 v[198:199], s[16:17], 0, v[128:129]
	s_mov_b32 m0, s25
	s_nop 0
	global_load_lds_dwordx4 v[198:199], off
	s_waitcnt lgkmcnt(8)
	s_barrier
; #define PG8_STAGE(bufoff, gbase, voff) do { _Pragma("unroll") for (int _i = 0; _i < 2; ++_i) \
;         __builtin_amdgcn_global_load_lds((const unsigned*)((const char*)(gbase) + (voff)[_i]), (LAS unsigned*)(lds + (bufoff) + ldsw + _i * 8192), 16, 0, 0); } while (0)
; #define PG8_LDA(dst, b, h) do { _Pragma("unroll") for (int m = 0; m < 4; ++m) _Pragma("unroll") for (int k = 0; k < 2; ++k) dst[m][k] = *(const LAS bf16x8*)(lds + PG8_SA(b, h) + aoff + m * 2048 + k * 1024); } while (0)
; #define PG8_LDB(dst, b, h) do { _Pragma("unroll") for (int n = 0; n < 2; ++n) _Pragma("unroll") for (int k = 0; k < 2; ++k) dst[n][k] = *(const LAS bf16x8*)(lds + PG8_SB(b, h) + boff + n * 2048 + k * 1024); } while (0)
; #define PG8_MMA(ai, bj, At, Bt) do { __builtin_amdgcn_s_setprio(1); _Pragma("unroll") for (int m = 0; m < 4; ++m) _Pragma("unroll") for (int n = 0; n < 2; ++n) _Pragma("unroll") for (int k = 0; k < 2; ++k) \
;         acc[ai][bj][m][n] = MmaOp<Epi::I8>::run(Bt[n][k], At[m][k], acc[ai][bj][m][n]); __builtin_amdgcn_s_setprio(0); } while (0)
; #define PG8_WAIT_V(n) asm volatile("s_waitcnt vmcnt(" #n ")" ::: "memory")
; #define PG8_WAIT_L(n) asm volatile("s_waitcnt lgkmcnt(" #n ")" ::: "memory")
; #define PG8_BAR __builtin_amdgcn_s_barrier()
; #define PG8_SCHED __builtin_amdgcn_sched_barrier(0)
; template <class Epi, class Sched>
; __device__ __forceinline__ void gemm_phase(LAS unsigned char* lds, const Gemm g, const Sched& S, const Epi& E) {
;     ...
;             PG8_WAIT_L(8); PG8_BAR; PG8_WAIT_L(0); PG8_MMA(0, 0, At, B0); PG8_BAR; PG8_SCHED;
;             PG8_LDB(B1, 1, 1); PG8_STAGE(PG8_SB(1, 0), b3, voffB);
;             PG8_BAR; PG8_WAIT_L(0); PG8_MMA(0, 1, At, B1); PG8_BAR;
;             PG8_LDA(At, 1, 1); PG8_STAGE(PG8_SA(1, 0), a3, voffA);
;             PG8_BAR; PG8_WAIT_L(0); PG8_MMA(1, 0, At, B0); PG8_BAR; PG8_SCHED;
;             PG8_STAGE(PG8_SB(1, 1), b3 + hstepB, voffB);
;             PG8_WAIT_V(6); PG8_BAR; PG8_MMA(1, 1, At, B1); PG8_BAR;
	s_waitcnt lgkmcnt(0)
	s_setprio 1
	s_waitcnt lgkmcnt(0)
	v_mfma_f32_16x16x32_bf16 v[124:127], v[140:143], v[164:167], v[124:127]
	v_mfma_f32_16x16x32_bf16 v[120:123], v[156:159], v[164:167], v[120:123]
	v_mfma_f32_16x16x32_bf16 v[116:119], v[140:143], v[172:175], v[116:119]
	v_mfma_f32_16x16x32_bf16 v[112:115], v[156:159], v[172:175], v[112:115]
	v_mfma_f32_16x16x32_bf16 v[92:95], v[140:143], v[182:185], v[92:95]
	v_mfma_f32_16x16x32_bf16 v[88:91], v[156:159], v[182:185], v[88:91]
	v_mfma_f32_16x16x32_bf16 v[84:87], v[140:143], v[190:193], v[84:87]
	v_mfma_f32_16x16x32_bf16 v[80:83], v[156:159], v[190:193], v[80:83]
	v_mfma_f32_16x16x32_bf16 v[124:127], v[152:155], v[168:171], v[124:127]
	v_mfma_f32_16x16x32_bf16 v[120:123], v[160:163], v[168:171], v[120:123]
	v_mfma_f32_16x16x32_bf16 v[116:119], v[152:155], v[178:181], v[116:119]
	v_mfma_f32_16x16x32_bf16 v[112:115], v[160:163], v[178:181], v[112:115]
	v_mfma_f32_16x16x32_bf16 v[92:95], v[152:155], v[186:189], v[92:95]
	v_mfma_f32_16x16x32_bf16 v[88:91], v[160:163], v[186:189], v[88:91]
	v_mfma_f32_16x16x32_bf16 v[84:87], v[152:155], v[194:197], v[84:87]
	v_mfma_f32_16x16x32_bf16 v[80:83], v[160:163], v[194:197], v[80:83]
	s_setprio 0
	s_barrier
	s_add_i32 s16, 0, 0x1c000
	s_add_i32 s17, s46, s19
	v_add_u32_e32 v177, s16, v147
	v_lshl_add_u64 v[144:145], v[144:145], 0, s[8:9]
	s_mov_b32 m0, s17
	ds_read_b128 v[198:201], v177
	ds_read_b128 v[202:205], v177 offset:1024
	ds_read_b128 v[206:209], v177 offset:2048
	ds_read_b128 v[210:213], v177 offset:3072
	global_load_lds_dwordx4 v[144:145], off
	v_lshl_add_u64 v[144:145], v[214:215], 0, s[8:9]
	s_add_i32 m0, s17, 0x2000
	s_nop 0
	global_load_lds_dwordx4 v[144:145], off
	s_barrier
	s_waitcnt lgkmcnt(0)
	s_setprio 1
	s_waitcnt lgkmcnt(0)
	v_mfma_f32_16x16x32_bf16 v[108:111], v[198:201], v[164:167], v[108:111]
	v_mfma_f32_16x16x32_bf16 v[104:107], v[206:209], v[164:167], v[104:107]
	v_mfma_f32_16x16x32_bf16 v[100:103], v[198:201], v[172:175], v[100:103]
	v_mfma_f32_16x16x32_bf16 v[96:99], v[206:209], v[172:175], v[96:99]
	v_mfma_f32_16x16x32_bf16 v[76:79], v[198:201], v[182:185], v[76:79]
	v_mfma_f32_16x16x32_bf16 v[72:75], v[206:209], v[182:185], v[72:75]
	v_mfma_f32_16x16x32_bf16 v[68:71], v[198:201], v[190:193], v[68:71]
	v_mfma_f32_16x16x32_bf16 v[64:67], v[206:209], v[190:193], v[64:67]
	v_mfma_f32_16x16x32_bf16 v[108:111], v[202:205], v[168:171], v[108:111]
	v_mfma_f32_16x16x32_bf16 v[104:107], v[210:213], v[168:171], v[104:107]
	v_mfma_f32_16x16x32_bf16 v[100:103], v[202:205], v[178:181], v[100:103]
	v_mfma_f32_16x16x32_bf16 v[96:99], v[210:213], v[178:181], v[96:99]
	v_mfma_f32_16x16x32_bf16 v[76:79], v[202:205], v[186:189], v[76:79]
	v_mfma_f32_16x16x32_bf16 v[72:75], v[210:213], v[186:189], v[72:75]
	v_mfma_f32_16x16x32_bf16 v[68:71], v[202:205], v[194:197], v[68:71]
	v_mfma_f32_16x16x32_bf16 v[64:67], v[210:213], v[194:197], v[64:67]
	s_setprio 0
	s_mov_b32 m0, s27
	v_lshl_add_u64 v[144:145], v[216:217], 0, s[8:9]
	s_barrier
	ds_read_b128 v[164:167], v150 offset:49152
	ds_read_b128 v[168:171], v150 offset:50176
	ds_read_b128 v[172:175], v150 offset:51200
	ds_read_b128 v[178:181], v150 offset:52224
	ds_read_b128 v[182:185], v150 offset:53248
	ds_read_b128 v[186:189], v150 offset:54272
	ds_read_b128 v[190:193], v150 offset:55296
	ds_read_b128 v[194:197], v150 offset:56320
	global_load_lds_dwordx4 v[144:145], off
	v_lshl_add_u64 v[144:145], v[218:219], 0, s[8:9]
	s_mov_b32 m0, s28
	s_nop 0
	global_load_lds_dwordx4 v[144:145], off
	s_barrier
	s_waitcnt lgkmcnt(0)
	s_setprio 1
	s_waitcnt lgkmcnt(0)
	v_mfma_f32_16x16x32_bf16 v[60:63], v[140:143], v[164:167], v[60:63]
	v_mfma_f32_16x16x32_bf16 v[56:59], v[156:159], v[164:167], v[56:59]
	v_mfma_f32_16x16x32_bf16 v[52:55], v[140:143], v[172:175], v[52:55]
	v_mfma_f32_16x16x32_bf16 v[48:51], v[156:159], v[172:175], v[48:51]
	v_mfma_f32_16x16x32_bf16 v[28:31], v[140:143], v[182:185], v[28:31]
	v_mfma_f32_16x16x32_bf16 v[24:27], v[156:159], v[182:185], v[24:27]
	v_mfma_f32_16x16x32_bf16 v[20:23], v[140:143], v[190:193], v[20:23]
	v_mfma_f32_16x16x32_bf16 v[16:19], v[156:159], v[190:193], v[16:19]
	v_mfma_f32_16x16x32_bf16 v[60:63], v[152:155], v[168:171], v[60:63]
	v_mfma_f32_16x16x32_bf16 v[56:59], v[160:163], v[168:171], v[56:59]
	v_mfma_f32_16x16x32_bf16 v[52:55], v[152:155], v[178:181], v[52:55]
	v_mfma_f32_16x16x32_bf16 v[48:51], v[160:163], v[178:181], v[48:51]
	v_mfma_f32_16x16x32_bf16 v[28:31], v[152:155], v[186:189], v[28:31]
	v_mfma_f32_16x16x32_bf16 v[24:27], v[160:163], v[186:189], v[24:27]
	v_mfma_f32_16x16x32_bf16 v[20:23], v[152:155], v[194:197], v[20:23]
	v_mfma_f32_16x16x32_bf16 v[16:19], v[160:163], v[194:197], v[16:19]
	s_setprio 0
	s_barrier
	s_add_u32 s14, s14, 0x158080
	s_addc_u32 s15, s15, 0
	s_add_i32 s16, s16, s19
	v_lshl_add_u64 v[140:141], s[14:15], 0, v[130:131]
	s_mov_b32 m0, s16
	s_nop 0
	global_load_lds_dwordx4 v[140:141], off
	v_lshl_add_u64 v[140:141], s[14:15], 0, v[128:129]
	s_add_i32 m0, s16, 0x2000
	s_nop 0
	global_load_lds_dwordx4 v[140:141], off
	s_waitcnt vmcnt(6)
	s_barrier
; __device__ __forceinline__ unsigned cvt_pk_bf16(float lo, float hi) { unsigned r; asm volatile("v_cvt_pk_bf16_f32 %0, %1, %2" : "=v"(r) : "v"(lo), "v"(hi)); return r; }
; #define PG8_BAR __builtin_amdgcn_s_barrier()
;     __device__ __forceinline__ void operator()(const f32x4 (&acc)[2][2][4][2], const Unit& u, int wr, int wc, int fr, int fq) const {
;         const int row0 = u.pm * BM + wr * 64 + fr, col0 = u.pn * BM + wc * 32 + 4 * fq;
;         const float* base = ((u.pm < MP / BM) ? base_lo : base_hi - (size_t)MP * DM) + (size_t)row0 * DM + col0;
;         f32x4 b[2][2], nb[2][2];
; #pragma unroll
;         for (int bj = 0; bj < 2; ++bj)
; #pragma unroll
;             for (int n = 0; n < 2; ++n) b[bj][n] = *(const f32x4*)(base + bj * HALF + n * 16);
; #pragma unroll
;         for (int g = 0; g < 8; ++g) {
;             const int ai = g >> 2, m = g & 3;
;             const int r = row0 + ai * HALF + m * 16; const size_t off = (size_t)r * DM + col0; float s = 0.f;
;             if (g < 7) { const float* nrow = base + (size_t)(((g + 1) >> 2) * HALF + ((g + 1) & 3) * 16) * DM;
; #pragma unroll
;                 for (int bj = 0; bj < 2; ++bj)
; #pragma unroll
;                     for (int n = 0; n < 2; ++n) nb[bj][n] = *(const f32x4*)(nrow + bj * HALF + n * 16); }
; #pragma unroll
;             for (int bj = 0; bj < 2; ++bj)
; #pragma unroll
;                 for (int n = 0; n < 2; ++n) {
;                     const f32x4 o = b[bj][n] + acc[ai][bj][m][n] * alpha;
;                     *(f32x4*)(out + off + bj * HALF + n * 16) = o;
;                     if (WITH_SSQ) s += (o[0] * o[0] + o[1] * o[1]) + (o[2] * o[2] + o[3] * o[3]);
;                     if (WITH_HB) { u32x2 w; w.x = cvt_pk_bf16(o[0], o[1]); w.y = cvt_pk_bf16(o[2], o[3]); *(u32x2*)(hb + off + bj * HALF + n * 16) = w; }
;                 }
;             if (WITH_SSQ) { s += __shfl_xor(s, 16); s += __shfl_xor(s, 32); if (fq == 0) atomicAdd(ssq + r, s); }
;             asm volatile("" ::: "memory");
; #pragma unroll
;             for (int bj = 0; bj < 2; ++bj)
; #pragma unroll
;                 for (int n = 0; n < 2; ++n) b[bj][n] = nb[bj][n];
;         }
;     }
; template <class Epi, class Sched>
; __device__ __forceinline__ void gemm_phase(LAS unsigned char* lds, const Gemm g, const Sched& S, const Epi& E) {
;     ...
;             PG8_WAIT_V(6); PG8_BAR; PG8_MMA(1, 1, At, B1); PG8_BAR;
;         }
	s_setprio 1
	v_mfma_f32_16x16x32_bf16 v[44:47], v[198:201], v[164:167], v[44:47]
	v_mfma_f32_16x16x32_bf16 v[40:43], v[206:209], v[164:167], v[40:43]
	v_mfma_f32_16x16x32_bf16 v[36:39], v[198:201], v[172:175], v[36:39]
	v_mfma_f32_16x16x32_bf16 v[32:35], v[206:209], v[172:175], v[32:35]
	v_mfma_f32_16x16x32_bf16 v[12:15], v[198:201], v[182:185], v[12:15]
	v_mfma_f32_16x16x32_bf16 v[8:11], v[206:209], v[182:185], v[8:11]
	v_mfma_f32_16x16x32_bf16 v[4:7], v[198:201], v[190:193], v[4:7]
	v_mfma_f32_16x16x32_bf16 v[0:3], v[206:209], v[190:193], v[0:3]
	v_mfma_f32_16x16x32_bf16 v[44:47], v[202:205], v[168:171], v[44:47]
	v_mfma_f32_16x16x32_bf16 v[40:43], v[210:213], v[168:171], v[40:43]
	v_mfma_f32_16x16x32_bf16 v[36:39], v[202:205], v[178:181], v[36:39]
	v_mfma_f32_16x16x32_bf16 v[32:35], v[210:213], v[178:181], v[32:35]
	v_mfma_f32_16x16x32_bf16 v[12:15], v[202:205], v[186:189], v[12:15]
	v_mfma_f32_16x16x32_bf16 v[8:11], v[210:213], v[186:189], v[8:11]
	v_mfma_f32_16x16x32_bf16 v[4:7], v[202:205], v[194:197], v[4:7]
	v_mfma_f32_16x16x32_bf16 v[0:3], v[210:213], v[194:197], v[0:3]
	s_setprio 0
	s_add_i32 s45, s45, 2
	s_add_u32 s12, s12, 0x100
	s_addc_u32 s13, s13, 0
	s_add_u32 s43, s43, 0x100
	s_addc_u32 s44, s44, 0
	s_cmpk_gt_u32 s45, 0x53
	s_barrier
	s_cbranch_scc0 .LBB0_936
	v_lshl_add_u32 v140, s41, 8, v146
	v_lshl_or_b32 v142, s42, 8, v148
	v_ashrrev_i32_e32 v141, 31, v140
	v_lshlrev_b64 v[144:145], 13, v[140:141]
	v_ashrrev_i32_e32 v143, 31, v142
	v_lshl_add_u64 v[144:145], s[68:69], 0, v[144:145]
	v_lshlrev_b64 v[142:143], 2, v[142:143]
	v_lshl_add_u64 v[144:145], v[144:145], 0, v[142:143]
	v_mov_b32_e32 v232, 0x20000
	v_mov_b32_e32 v233, 0
	v_lshl_add_u64 v[218:219], v[144:145], 0, v[232:233]
	v_mov_b32_e32 v232, 0x40000
	v_lshl_add_u64 v[220:221], v[144:145], 0, v[232:233]
	v_mov_b32_e32 v232, 0x60000
	v_lshl_add_u64 v[222:223], v[144:145], 0, v[232:233]
	v_mov_b32_e32 v232, 0x100000
	v_lshl_add_u64 v[224:225], v[144:145], 0, v[232:233]
	v_mov_b32_e32 v232, 0x120000
	v_lshl_add_u64 v[226:227], v[144:145], 0, v[232:233]
	v_mov_b32_e32 v232, 0x140000
	v_lshl_add_u64 v[228:229], v[144:145], 0, v[232:233]
	v_mov_b32_e32 v232, 0x160000
	v_lshl_add_u64 v[230:231], v[144:145], 0, v[232:233]
	global_load_dwordx4 v[152:155], v[144:145], off
	global_load_dwordx4 v[156:159], v[144:145], off offset:64
	global_load_dwordx4 v[160:163], v[144:145], off offset:512
	global_load_dwordx4 v[164:167], v[144:145], off offset:576
	global_load_dwordx4 v[168:171], v[218:219], off
	global_load_dwordx4 v[172:175], v[218:219], off offset:64
	global_load_dwordx4 v[178:181], v[218:219], off offset:512
	global_load_dwordx4 v[182:185], v[218:219], off offset:576
	global_load_dwordx4 v[186:189], v[220:221], off
	global_load_dwordx4 v[190:193], v[220:221], off offset:64
	global_load_dwordx4 v[194:197], v[220:221], off offset:512
	global_load_dwordx4 v[198:201], v[220:221], off offset:576
	global_load_dwordx4 v[202:205], v[222:223], off
	global_load_dwordx4 v[206:209], v[222:223], off offset:64
	global_load_dwordx4 v[210:213], v[222:223], off offset:512
	global_load_dwordx4 v[214:217], v[222:223], off offset:576
	s_mov_b32 s42, s39
	s_mov_b32 s41, s40
	s_mov_b64 s[14:15], s[6:7]
	s_mov_b64 s[12:13], s[4:5]
	s_waitcnt vmcnt(12)
	v_pk_fma_f32 v[124:125], v[124:125], 0.5, v[152:153] op_sel_hi:[1,0,1]
	v_pk_fma_f32 v[126:127], v[126:127], 0.5, v[154:155] op_sel_hi:[1,0,1]
	v_pk_fma_f32 v[120:121], v[120:121], 0.5, v[156:157] op_sel_hi:[1,0,1]
	v_pk_fma_f32 v[122:123], v[122:123], 0.5, v[158:159] op_sel_hi:[1,0,1]
	v_pk_fma_f32 v[108:109], v[108:109], 0.5, v[160:161] op_sel_hi:[1,0,1]
	v_pk_fma_f32 v[110:111], v[110:111], 0.5, v[162:163] op_sel_hi:[1,0,1]
	v_pk_fma_f32 v[104:105], v[104:105], 0.5, v[164:165] op_sel_hi:[1,0,1]
	v_pk_fma_f32 v[106:107], v[106:107], 0.5, v[166:167] op_sel_hi:[1,0,1]
	global_store_dwordx4 v[144:145], v[124:127], off
	global_store_dwordx4 v[144:145], v[120:123], off offset:64
	global_store_dwordx4 v[144:145], v[108:111], off offset:512
	global_store_dwordx4 v[144:145], v[104:107], off offset:576
	global_load_dwordx4 v[152:155], v[224:225], off
	global_load_dwordx4 v[156:159], v[224:225], off offset:64
	global_load_dwordx4 v[160:163], v[224:225], off offset:512
	global_load_dwordx4 v[164:167], v[224:225], off offset:576
	s_waitcnt vmcnt(16)
	v_pk_fma_f32 v[116:117], v[116:117], 0.5, v[168:169] op_sel_hi:[1,0,1]
	v_pk_fma_f32 v[118:119], v[118:119], 0.5, v[170:171] op_sel_hi:[1,0,1]
	v_pk_fma_f32 v[112:113], v[112:113], 0.5, v[172:173] op_sel_hi:[1,0,1]
	v_pk_fma_f32 v[114:115], v[114:115], 0.5, v[174:175] op_sel_hi:[1,0,1]
	v_pk_fma_f32 v[100:101], v[100:101], 0.5, v[178:179] op_sel_hi:[1,0,1]
	v_pk_fma_f32 v[102:103], v[102:103], 0.5, v[180:181] op_sel_hi:[1,0,1]
	v_pk_fma_f32 v[96:97], v[96:97], 0.5, v[182:183] op_sel_hi:[1,0,1]
	v_pk_fma_f32 v[98:99], v[98:99], 0.5, v[184:185] op_sel_hi:[1,0,1]
	global_store_dwordx4 v[218:219], v[116:119], off
	global_store_dwordx4 v[218:219], v[112:115], off offset:64
	global_store_dwordx4 v[218:219], v[100:103], off offset:512
	global_store_dwordx4 v[218:219], v[96:99], off offset:576
	global_load_dwordx4 v[168:171], v[226:227], off
	global_load_dwordx4 v[172:175], v[226:227], off offset:64
	global_load_dwordx4 v[178:181], v[226:227], off offset:512
	global_load_dwordx4 v[182:185], v[226:227], off offset:576
	s_waitcnt vmcnt(20)
; __device__ __forceinline__ unsigned cvt_pk_bf16(float lo, float hi) { unsigned r; asm volatile("v_cvt_pk_bf16_f32 %0, %1, %2" : "=v"(r) : "v"(lo), "v"(hi)); return r; }
; #define PG8_WAIT_V(n) asm volatile("s_waitcnt vmcnt(" #n ")" ::: "memory")
; #define PG8_BAR __builtin_amdgcn_s_barrier()
;     __device__ __forceinline__ void operator()(const f32x4 (&acc)[2][2][4][2], const Unit& u, int wr, int wc, int fr, int fq) const {
;     ...
;         for (int g = 0; g < 8; ++g) {
;             const int ai = g >> 2, m = g & 3;
;             const int r = row0 + ai * HALF + m * 16; const size_t off = (size_t)r * DM + col0; float s = 0.f;
;             if (g < 7) { const float* nrow = base + (size_t)(((g + 1) >> 2) * HALF + ((g + 1) & 3) * 16) * DM;
; #pragma unroll
;                 for (int bj = 0; bj < 2; ++bj)
; #pragma unroll
;                     for (int n = 0; n < 2; ++n) nb[bj][n] = *(const f32x4*)(nrow + bj * HALF + n * 16); }
; #pragma unroll
;             for (int bj = 0; bj < 2; ++bj)
; #pragma unroll
;                 for (int n = 0; n < 2; ++n) {
;                     const f32x4 o = b[bj][n] + acc[ai][bj][m][n] * alpha;
;                     *(f32x4*)(out + off + bj * HALF + n * 16) = o;
;                     if (WITH_SSQ) s += (o[0] * o[0] + o[1] * o[1]) + (o[2] * o[2] + o[3] * o[3]);
;                     if (WITH_HB) { u32x2 w; w.x = cvt_pk_bf16(o[0], o[1]); w.y = cvt_pk_bf16(o[2], o[3]); *(u32x2*)(hb + off + bj * HALF + n * 16) = w; }
;                 }
;             if (WITH_SSQ) { s += __shfl_xor(s, 16); s += __shfl_xor(s, 32); if (fq == 0) atomicAdd(ssq + r, s); }
;             asm volatile("" ::: "memory");
; #pragma unroll
;             for (int bj = 0; bj < 2; ++bj)
; #pragma unroll
;                 for (int n = 0; n < 2; ++n) b[bj][n] = nb[bj][n];
;         }
;     }
; template <class Epi, class Sched>
; __device__ __forceinline__ void gemm_phase(LAS unsigned char* lds, const Gemm g, const Sched& S, const Epi& E) {
;     ...
;     PG8_WAIT_V(0);
;     if (wr == 0) PG8_BAR;
;     PG8_BAR;
	v_pk_fma_f32 v[92:93], v[92:93], 0.5, v[186:187] op_sel_hi:[1,0,1]
	v_pk_fma_f32 v[94:95], v[94:95], 0.5, v[188:189] op_sel_hi:[1,0,1]
	v_pk_fma_f32 v[88:89], v[88:89], 0.5, v[190:191] op_sel_hi:[1,0,1]
	v_pk_fma_f32 v[90:91], v[90:91], 0.5, v[192:193] op_sel_hi:[1,0,1]
	v_pk_fma_f32 v[76:77], v[76:77], 0.5, v[194:195] op_sel_hi:[1,0,1]
	v_pk_fma_f32 v[78:79], v[78:79], 0.5, v[196:197] op_sel_hi:[1,0,1]
	v_pk_fma_f32 v[72:73], v[72:73], 0.5, v[198:199] op_sel_hi:[1,0,1]
	v_pk_fma_f32 v[74:75], v[74:75], 0.5, v[200:201] op_sel_hi:[1,0,1]
	global_store_dwordx4 v[220:221], v[92:95], off
	global_store_dwordx4 v[220:221], v[88:91], off offset:64
	global_store_dwordx4 v[220:221], v[76:79], off offset:512
	global_store_dwordx4 v[220:221], v[72:75], off offset:576
	global_load_dwordx4 v[186:189], v[228:229], off
	global_load_dwordx4 v[190:193], v[228:229], off offset:64
	global_load_dwordx4 v[194:197], v[228:229], off offset:512
	global_load_dwordx4 v[198:201], v[228:229], off offset:576
	s_waitcnt vmcnt(24)
	v_pk_fma_f32 v[84:85], v[84:85], 0.5, v[202:203] op_sel_hi:[1,0,1]
	v_pk_fma_f32 v[86:87], v[86:87], 0.5, v[204:205] op_sel_hi:[1,0,1]
	v_pk_fma_f32 v[80:81], v[80:81], 0.5, v[206:207] op_sel_hi:[1,0,1]
	v_pk_fma_f32 v[82:83], v[82:83], 0.5, v[208:209] op_sel_hi:[1,0,1]
	v_pk_fma_f32 v[68:69], v[68:69], 0.5, v[210:211] op_sel_hi:[1,0,1]
	v_pk_fma_f32 v[70:71], v[70:71], 0.5, v[212:213] op_sel_hi:[1,0,1]
	v_pk_fma_f32 v[64:65], v[64:65], 0.5, v[214:215] op_sel_hi:[1,0,1]
	v_pk_fma_f32 v[66:67], v[66:67], 0.5, v[216:217] op_sel_hi:[1,0,1]
	global_store_dwordx4 v[222:223], v[84:87], off
	global_store_dwordx4 v[222:223], v[80:83], off offset:64
	global_store_dwordx4 v[222:223], v[68:71], off offset:512
	global_store_dwordx4 v[222:223], v[64:67], off offset:576
	global_load_dwordx4 v[202:205], v[230:231], off
	global_load_dwordx4 v[206:209], v[230:231], off offset:64
	global_load_dwordx4 v[210:213], v[230:231], off offset:512
	global_load_dwordx4 v[214:217], v[230:231], off offset:576
	s_waitcnt vmcnt(24)
	v_pk_fma_f32 v[60:61], v[60:61], 0.5, v[152:153] op_sel_hi:[1,0,1]
	v_pk_fma_f32 v[62:63], v[62:63], 0.5, v[154:155] op_sel_hi:[1,0,1]
	v_pk_fma_f32 v[56:57], v[56:57], 0.5, v[156:157] op_sel_hi:[1,0,1]
	v_pk_fma_f32 v[58:59], v[58:59], 0.5, v[158:159] op_sel_hi:[1,0,1]
	v_pk_fma_f32 v[44:45], v[44:45], 0.5, v[160:161] op_sel_hi:[1,0,1]
	v_pk_fma_f32 v[46:47], v[46:47], 0.5, v[162:163] op_sel_hi:[1,0,1]
	v_pk_fma_f32 v[40:41], v[40:41], 0.5, v[164:165] op_sel_hi:[1,0,1]
	v_pk_fma_f32 v[42:43], v[42:43], 0.5, v[166:167] op_sel_hi:[1,0,1]
	global_store_dwordx4 v[224:225], v[60:63], off
	global_store_dwordx4 v[224:225], v[56:59], off offset:64
	global_store_dwordx4 v[224:225], v[44:47], off offset:512
	global_store_dwordx4 v[224:225], v[40:43], off offset:576
	s_waitcnt vmcnt(20)
	v_pk_fma_f32 v[52:53], v[52:53], 0.5, v[168:169] op_sel_hi:[1,0,1]
	v_pk_fma_f32 v[54:55], v[54:55], 0.5, v[170:171] op_sel_hi:[1,0,1]
	v_pk_fma_f32 v[48:49], v[48:49], 0.5, v[172:173] op_sel_hi:[1,0,1]
	v_pk_fma_f32 v[50:51], v[50:51], 0.5, v[174:175] op_sel_hi:[1,0,1]
	v_pk_fma_f32 v[36:37], v[36:37], 0.5, v[178:179] op_sel_hi:[1,0,1]
	v_pk_fma_f32 v[38:39], v[38:39], 0.5, v[180:181] op_sel_hi:[1,0,1]
	v_pk_fma_f32 v[32:33], v[32:33], 0.5, v[182:183] op_sel_hi:[1,0,1]
	v_pk_fma_f32 v[34:35], v[34:35], 0.5, v[184:185] op_sel_hi:[1,0,1]
	global_store_dwordx4 v[226:227], v[52:55], off
	global_store_dwordx4 v[226:227], v[48:51], off offset:64
	global_store_dwordx4 v[226:227], v[36:39], off offset:512
	global_store_dwordx4 v[226:227], v[32:35], off offset:576
	s_waitcnt vmcnt(16)
	v_pk_fma_f32 v[28:29], v[28:29], 0.5, v[186:187] op_sel_hi:[1,0,1]
	v_pk_fma_f32 v[30:31], v[30:31], 0.5, v[188:189] op_sel_hi:[1,0,1]
	v_pk_fma_f32 v[24:25], v[24:25], 0.5, v[190:191] op_sel_hi:[1,0,1]
	v_pk_fma_f32 v[26:27], v[26:27], 0.5, v[192:193] op_sel_hi:[1,0,1]
	v_pk_fma_f32 v[12:13], v[12:13], 0.5, v[194:195] op_sel_hi:[1,0,1]
	v_pk_fma_f32 v[14:15], v[14:15], 0.5, v[196:197] op_sel_hi:[1,0,1]
	v_pk_fma_f32 v[8:9], v[8:9], 0.5, v[198:199] op_sel_hi:[1,0,1]
	v_pk_fma_f32 v[10:11], v[10:11], 0.5, v[200:201] op_sel_hi:[1,0,1]
	global_store_dwordx4 v[228:229], v[28:31], off
	global_store_dwordx4 v[228:229], v[24:27], off offset:64
	global_store_dwordx4 v[228:229], v[12:15], off offset:512
	global_store_dwordx4 v[228:229], v[8:11], off offset:576
	s_waitcnt vmcnt(12)
	v_pk_fma_f32 v[20:21], v[20:21], 0.5, v[202:203] op_sel_hi:[1,0,1]
	v_pk_fma_f32 v[22:23], v[22:23], 0.5, v[204:205] op_sel_hi:[1,0,1]
	v_pk_fma_f32 v[16:17], v[16:17], 0.5, v[206:207] op_sel_hi:[1,0,1]
	v_pk_fma_f32 v[18:19], v[18:19], 0.5, v[208:209] op_sel_hi:[1,0,1]
	v_pk_fma_f32 v[4:5], v[4:5], 0.5, v[210:211] op_sel_hi:[1,0,1]
	v_pk_fma_f32 v[6:7], v[6:7], 0.5, v[212:213] op_sel_hi:[1,0,1]
	v_pk_fma_f32 v[0:1], v[0:1], 0.5, v[214:215] op_sel_hi:[1,0,1]
	v_pk_fma_f32 v[2:3], v[2:3], 0.5, v[216:217] op_sel_hi:[1,0,1]
	global_store_dwordx4 v[230:231], v[20:23], off
	global_store_dwordx4 v[230:231], v[16:19], off offset:64
	global_store_dwordx4 v[230:231], v[4:7], off offset:512
	global_store_dwordx4 v[230:231], v[0:3], off offset:576
	s_and_b64 vcc, exec, s[0:1]
	s_cbranch_vccz .LBB0_929
	s_waitcnt vmcnt(0)
	s_cmpk_gt_u32 s18, 0xff
	s_cbranch_scc1 .LBB0_940
	s_barrier
